# merge task remap variant: each XCD owns 16 row-tiles; per round 8 row-tiles x 4 column-tiles
# speedup vs baseline: 1.0008x; 1.0008x over previous
; template <bool RFA, bool RFB, class LA, class LB, class EPI>
; DI void gemm_tile2s(u16* smem, int nk, LA la, LB lb, EPI epi) {
;   const int tid = tidx(), lane = tid & 63, wave = tid >> 6;
;   const int wm = wave >> 2, wn = wave & 3, lr = lane & 31, lh = lane >> 5;
;   u16* As = smem;
;   u16* Bs = smem + 2 * TILE_ELEMS;
;   f32x16 acc[2];
;   acc[0] = zero16(); acc[1] = zero16();
;   u32x4 ra0[2], rb0[2], ra1[2], rb1[2];
;   auto ld = [&](u32x4 (&ra)[2], u32x4 (&rb)[2], int kt) __attribute__((always_inline)) {
;     const int k0 = kt * 64;
; #pragma unroll
;     for (int i = 0; i < 2; ++i) { const int c = tid + NTH * i; ra[i] = la(A_ROW(c), k0 + A_KC(c) * 8); rb[i] = lb(B_ROW(c), k0 + B_KC(c) * 8); }
;   };
;   auto stl = [&](u32x4 (&ra)[2], u32x4 (&rb)[2], int buf) __attribute__((always_inline)) {
; #pragma unroll
;     for (int i = 0; i < 2; ++i) {
;       const int c = tid + NTH * i;
;       *(u32x4*)(As + buf * TILE_ELEMS + A_ROW(c) * LDT + A_KC(c) * 8) = ra[i];
;       *(u32x4*)(Bs + buf * TILE_ELEMS + B_ROW(c) * LDT + B_KC(c) * 8) = rb[i];
;     }
;   };
;   auto compute = [&](int buf) __attribute__((always_inline)) {
;     const u16* Ab = As + buf * TILE_ELEMS + (wm * 64 + lr) * LDT + lh * 8;
;     const u16* Bb = Bs + buf * TILE_ELEMS + (wn * 32 + lr) * LDT + lh * 8;
; #pragma unroll
;     for (int ks = 0; ks < 4; ++ks) {
;       const bf16x8 a0 = *(const bf16x8*)(Ab + ks * 16);
;       const bf16x8 a1 = *(const bf16x8*)(Ab + 32 * LDT + ks * 16);
;       const bf16x8 b = *(const bf16x8*)(Bb + ks * 16);
;       acc[0] = mfma(a0, b, acc[0]);
;       acc[1] = mfma(a1, b, acc[1]);
;     }
;   };
;   ld(ra0, rb0, 0);
;   if (nk > 1) ld(ra1, rb1, 1);
;   stl(ra0, rb0, 0);
; DI void phase_merge(const Prm& p, u16* smem, int l, int& base) {
;   TASK_LOOP(t, 8 * 128, base) {
;     const int tn = t & 7, tm = t >> 3, n0 = tn * 128, m0 = tm * 128;
;     f32x16 macc[2];
;     macc[0] = zero16(); macc[1] = zero16();
;     merge_branch(p, smem, p.PaT + (size_t)l * 1024 * 768, p.UT, 768, 0, n0, m0, macc);
;     merge_branch(p, smem, p.PbT + (size_t)l * 1024 * 128, p.ob, 128, 1, n0, m0, macc);
;     ...
;     merge_branch(p, smem, p.PdT + (size_t)l * 1024 * 256, p.od, 256, 3, n0, m0, macc);
;     const int tid2 = tidx(), lane = tid2 & 63, wave = tid2 >> 6, wm = wave >> 2, wn = wave & 3, lr = lane & 31, lh = lane >> 5;
;     const int tok = m0 + wn * 32 + lr;
.LBB0_2250:
	v_readlane_b32 s36, v253, 28
	v_readlane_b32 s37, v253, 29
	v_readlane_b32 s38, v253, 30
	v_readlane_b32 s39, v253, 31
	v_readlane_b32 s40, v252, 4
	v_readlane_b32 s41, v252, 5
	v_readlane_b32 s42, v252, 6
	v_readlane_b32 s43, v252, 7
	v_readlane_b32 s48, v253, 20
	v_readlane_b32 s49, v253, 21
	v_and_b32_e32 v226, 7, v224
	v_lshlrev_b32_e32 v226, 4, v226
	v_lshrrev_b32_e32 v227, 3, v224
	v_and_b32_e32 v228, 0xffffffe3, v227
	v_lshrrev_b32_e32 v229, 1, v227
	v_and_b32_e32 v229, 12, v229
	v_or_b32_e32 v228, v228, v229
	v_lshlrev_b32_e32 v229, 2, v227
	v_and_b32_e32 v229, 16, v229
	v_or_b32_e32 v228, v228, v229
	s_movk_i32 s52, 0x600
	v_mad_u32_u24 v210, v228, s52, v226
	v_mad_u32_u24 v214, v227, s52, v226
	s_movk_i32 s52, 0x100
	v_mad_u32_u24 v211, v228, s52, v226
	v_mad_u32_u24 v215, v227, s52, v226
	s_movk_i32 s52, 0x300
	v_mad_u32_u24 v212, v228, s52, v226
	v_mad_u32_u24 v216, v227, s52, v226
	s_movk_i32 s52, 0x200
	v_mad_u32_u24 v213, v228, s52, v226
	v_mad_u32_u24 v217, v227, s52, v226
	s_movk_i32 s52, 0x90
	v_mad_u32_u24 v218, v227, s52, v226
	v_lshrrev_b32_e32 v226, 1, v224
	v_and_b32_e32 v227, 16, v226
	v_and_b32_e32 v228, 31, v224
	v_lshrrev_b32_e32 v229, 2, v224
	v_and_b32_e32 v229, 64, v229
	v_and_b32_e32 v226, 0x60, v226
	v_or_b32_e32 v226, v226, v228
	v_or_b32_e32 v228, v229, v228
	v_mad_u32_u24 v219, v228, s52, v227
	v_mad_u32_u24 v220, v226, s52, v227
	v_add_u32_e32 v220, 0xd800, v220
	v_add_u32_e32 v223, 0xd800, v218
	v_or_b32_e32 v229, v229, v227
	v_lshlrev_b32_e32 v229, 1, v229
	v_lshl_add_u32 v221, v226, 13, v229
	v_lshl_add_u32 v222, v226, 11, v229
	s_and_b32 s52, s31, 7
	s_lshl_b32 s52, s52, 4
	s_lshr_b32 s53, s31, 9
	s_lshl_b32 s53, s53, 3
	s_or_b32 s52, s52, s53
	s_bfe_u32 s53, s31, 0x30005
	s_or_b32 s52, s52, s53
	s_lshl_b32 s59, s52, 7
	s_bfe_u32 s52, s31, 0x10008
	s_lshl_b32 s52, s52, 2
	s_bfe_u32 s53, s31, 0x20003
	s_or_b32 s52, s52, s53
	s_lshl_b32 s58, s52, 7
	s_mul_i32 s52, s58, 0x600
	s_add_u32 s0, s16, s52
	s_addc_u32 s1, s17, 0
	s_add_u32 s2, s0, 0x18000
	s_addc_u32 s3, s1, 0
	s_mul_i32 s52, s59, 0x600
	s_add_u32 s4, s14, s52
	s_addc_u32 s5, s15, 0
	s_add_u32 s6, s4, 0x18000
	s_addc_u32 s7, s5, 0
	global_load_dwordx4 v[66:69], v210, s[0:1]
	global_load_dwordx4 v[70:73], v210, s[2:3]
	global_load_dwordx4 v[74:77], v214, s[4:5]
	global_load_dwordx4 v[78:81], v214, s[6:7]
	global_load_dwordx4 v[82:85], v210, s[0:1] offset:128
	global_load_dwordx4 v[86:89], v210, s[2:3] offset:128
	global_load_dwordx4 v[90:93], v214, s[4:5] offset:128
	global_load_dwordx4 v[94:97], v214, s[6:7] offset:128
	global_load_dwordx4 v[98:101], v210, s[0:1] offset:256
	global_load_dwordx4 v[102:105], v210, s[2:3] offset:256
	global_load_dwordx4 v[106:109], v214, s[4:5] offset:256
	global_load_dwordx4 v[110:113], v214, s[6:7] offset:256
	global_load_dwordx4 v[114:117], v210, s[0:1] offset:384
	global_load_dwordx4 v[118:121], v210, s[2:3] offset:384
	global_load_dwordx4 v[122:125], v214, s[4:5] offset:384
	global_load_dwordx4 v[126:129], v214, s[6:7] offset:384
	s_waitcnt vmcnt(8)
	ds_write_b128 v218, v[66:69]
	ds_write_b128 v218, v[70:73] offset:9216
	ds_write_b128 v223, v[74:77]
	ds_write_b128 v223, v[78:81] offset:9216
	ds_write_b128 v218, v[82:85] offset:18432
	ds_write_b128 v218, v[86:89] offset:27648
	ds_write_b128 v223, v[90:93] offset:18432
	ds_write_b128 v223, v[94:97] offset:27648
	global_load_dwordx4 v[66:69], v210, s[0:1] offset:512
	global_load_dwordx4 v[70:73], v210, s[2:3] offset:512
	global_load_dwordx4 v[74:77], v214, s[4:5] offset:512
	global_load_dwordx4 v[78:81], v214, s[6:7] offset:512
	global_load_dwordx4 v[82:85], v210, s[0:1] offset:640
	global_load_dwordx4 v[86:89], v210, s[2:3] offset:640
	global_load_dwordx4 v[90:93], v214, s[4:5] offset:640
	global_load_dwordx4 v[94:97], v214, s[6:7] offset:640
	s_waitcnt vmcnt(0)
	s_waitcnt lgkmcnt(0)
	s_barrier
	ds_read_b128 v[130:133], v219
	ds_read_b128 v[134:137], v220
	ds_read_b128 v[138:141], v219 offset:4608
	ds_read_b128 v[142:145], v219 offset:32
	ds_read_b128 v[146:149], v220 offset:32
	ds_read_b128 v[150:153], v219 offset:4640
	s_waitcnt lgkmcnt(0)
.Lmrg_task:
	s_lshl_b32 s52, s59, 13
	s_lshl_b32 s53, s58, 1
	s_add_u32 s52, s52, s53
	s_add_u32 s8, s42, s52
	s_addc_u32 s9, s43, 0
	s_add_u32 s10, s8, 0x1000
	s_addc_u32 s11, s9, 0
	s_lshl_b32 s52, s59, 11
	s_add_u32 s52, s52, s53
	s_add_u32 s12, s48, s52
	s_addc_u32 s13, s49, 0
	ds_read_b128 v[154:157], v219 offset:64
	ds_read_b128 v[158:161], v220 offset:64
	ds_read_b128 v[162:165], v219 offset:4672
	v_mfma_f32_32x32x16_bf16 v[18:33], v[130:133], v[134:137], 0
	ds_read_b128 v[166:169], v219 offset:96
	ds_read_b128 v[170:173], v220 offset:96
	ds_read_b128 v[174:177], v219 offset:4704
	v_mfma_f32_32x32x16_bf16 v[2:17], v[138:141], v[134:137], 0
	s_waitcnt vmcnt(16)
	ds_write_b128 v218, v[98:101] offset:36864
	ds_write_b128 v218, v[102:105] offset:46080
	v_mfma_f32_32x32x16_bf16 v[18:33], v[142:145], v[146:149], v[18:33]
	ds_write_b128 v223, v[106:109] offset:36864
	ds_write_b128 v223, v[110:113] offset:46080
	v_mfma_f32_32x32x16_bf16 v[2:17], v[150:153], v[146:149], v[2:17]
	global_load_dwordx4 v[98:101], v210, s[0:1] offset:768
	global_load_dwordx4 v[102:105], v210, s[2:3] offset:768
	global_load_dwordx4 v[106:109], v214, s[4:5] offset:768
	global_load_dwordx4 v[110:113], v214, s[6:7] offset:768
	ds_read_b128 v[130:133], v219 offset:18432
	ds_read_b128 v[134:137], v220 offset:18432
	ds_read_b128 v[138:141], v219 offset:23040
	s_waitcnt lgkmcnt(11)
	v_mfma_f32_32x32x16_bf16 v[18:33], v[154:157], v[158:161], v[18:33]
	ds_read_b128 v[142:145], v219 offset:18464
	ds_read_b128 v[146:149], v220 offset:18464
	ds_read_b128 v[150:153], v219 offset:23072
	s_waitcnt lgkmcnt(13)
	v_mfma_f32_32x32x16_bf16 v[2:17], v[162:165], v[158:161], v[2:17]
	s_waitcnt lgkmcnt(11)
	v_mfma_f32_32x32x16_bf16 v[18:33], v[166:169], v[170:173], v[18:33]
	s_waitcnt lgkmcnt(10)
	v_mfma_f32_32x32x16_bf16 v[2:17], v[174:177], v[170:173], v[2:17]
	s_waitcnt lgkmcnt(0)
	s_barrier
; DI f32x16 mfma(bf16x8 a, bf16x8 b, f32x16 c) { return __builtin_amdgcn_mfma_f32_32x32x16_bf16(a, b, c, 0, 0, 0); }
; template <bool RFA, bool RFB, class LA, class LB, class EPI>
; DI void gemm_tile2s(u16* smem, int nk, LA la, LB lb, EPI epi) {
;     ...
;   auto compute = [&](int buf) __attribute__((always_inline)) {
;     const u16* Ab = As + buf * TILE_ELEMS + (wm * 64 + lr) * LDT + lh * 8;
;     const u16* Bb = Bs + buf * TILE_ELEMS + (wn * 32 + lr) * LDT + lh * 8;
; #pragma unroll
;     for (int ks = 0; ks < 4; ++ks) {
;       const bf16x8 a0 = *(const bf16x8*)(Ab + ks * 16);
;       const bf16x8 a1 = *(const bf16x8*)(Ab + 32 * LDT + ks * 16);
;       const bf16x8 b = *(const bf16x8*)(Bb + ks * 16);
;       acc[0] = mfma(a0, b, acc[0]);
;       acc[1] = mfma(a1, b, acc[1]);
;     }
;   };
;   ld(ra0, rb0, 0);
;   if (nk > 1) ld(ra1, rb1, 1);
;   stl(ra0, rb0, 0);
;   if (nk > 2) ld(ra0, rb0, 2);
;   __syncthreads();
; #pragma unroll 1
;   for (int kt = 0; kt < nk; kt += 2) {
;     compute(0);
;     if (kt + 1 < nk) { stl(ra1, rb1, 1); if (kt + 3 < nk) ld(ra1, rb1, kt + 3); }
;     __syncthreads();
;     if (kt + 1 < nk) {
;       compute(1);
;       if (kt + 2 < nk) { stl(ra0, rb0, 0); if (kt + 4 < nk) ld(ra0, rb0, kt + 4); }
;       __syncthreads();
;     }
;   }
; template <class ACC>
; DI void merge_branch(const Prm& p, u16* smem, const u16* W, const u16* X, int ld, int bi, int n0, int m0, ACC& macc) {
;   auto la = [&](int row, int k) __attribute__((always_inline)) { return *(const u32x4*)(W + (size_t)(n0 + (row & ~31) + perm_m(row & 31)) * ld + k); };
;   auto lb = [&](int row, int k) __attribute__((always_inline)) { return *(const u32x4*)(X + (size_t)(m0 + row) * ld + k); };
	ds_read_b128 v[154:157], v219 offset:18496
	ds_read_b128 v[158:161], v220 offset:18496
	ds_read_b128 v[162:165], v219 offset:23104
	v_mfma_f32_32x32x16_bf16 v[18:33], v[130:133], v[134:137], v[18:33]
	ds_read_b128 v[166:169], v219 offset:18528
	ds_read_b128 v[170:173], v220 offset:18528
	ds_read_b128 v[174:177], v219 offset:23136
	v_mfma_f32_32x32x16_bf16 v[2:17], v[138:141], v[134:137], v[2:17]
	s_waitcnt vmcnt(16)
	ds_write_b128 v218, v[114:117]
	ds_write_b128 v218, v[118:121] offset:9216
	v_mfma_f32_32x32x16_bf16 v[18:33], v[142:145], v[146:149], v[18:33]
	ds_write_b128 v223, v[122:125]
	ds_write_b128 v223, v[126:129] offset:9216
	v_mfma_f32_32x32x16_bf16 v[2:17], v[150:153], v[146:149], v[2:17]
	global_load_dwordx4 v[114:117], v210, s[0:1] offset:896
	global_load_dwordx4 v[118:121], v210, s[2:3] offset:896
	global_load_dwordx4 v[122:125], v214, s[4:5] offset:896
	global_load_dwordx4 v[126:129], v214, s[6:7] offset:896
	ds_read_b128 v[130:133], v219 offset:36864
	ds_read_b128 v[134:137], v220 offset:36864
	ds_read_b128 v[138:141], v219 offset:41472
	s_waitcnt lgkmcnt(11)
	v_mfma_f32_32x32x16_bf16 v[18:33], v[154:157], v[158:161], v[18:33]
	ds_read_b128 v[142:145], v219 offset:36896
	ds_read_b128 v[146:149], v220 offset:36896
	ds_read_b128 v[150:153], v219 offset:41504
	s_waitcnt lgkmcnt(13)
	v_mfma_f32_32x32x16_bf16 v[2:17], v[162:165], v[158:161], v[2:17]
	s_waitcnt lgkmcnt(11)
	v_mfma_f32_32x32x16_bf16 v[18:33], v[166:169], v[170:173], v[18:33]
	s_waitcnt lgkmcnt(10)
	v_mfma_f32_32x32x16_bf16 v[2:17], v[174:177], v[170:173], v[2:17]
	s_waitcnt lgkmcnt(0)
	s_barrier
	ds_read_b128 v[154:157], v219 offset:36928
	ds_read_b128 v[158:161], v220 offset:36928
	ds_read_b128 v[162:165], v219 offset:41536
	v_mfma_f32_32x32x16_bf16 v[18:33], v[130:133], v[134:137], v[18:33]
	ds_read_b128 v[166:169], v219 offset:36960
	ds_read_b128 v[170:173], v220 offset:36960
	ds_read_b128 v[174:177], v219 offset:41568
	v_mfma_f32_32x32x16_bf16 v[2:17], v[138:141], v[134:137], v[2:17]
	s_waitcnt vmcnt(16)
	ds_write_b128 v218, v[66:69] offset:18432
	ds_write_b128 v218, v[70:73] offset:27648
	v_mfma_f32_32x32x16_bf16 v[18:33], v[142:145], v[146:149], v[18:33]
	ds_write_b128 v223, v[74:77] offset:18432
	ds_write_b128 v223, v[78:81] offset:27648
	v_mfma_f32_32x32x16_bf16 v[2:17], v[150:153], v[146:149], v[2:17]
	global_load_dwordx4 v[66:69], v210, s[0:1] offset:1024
	global_load_dwordx4 v[70:73], v210, s[2:3] offset:1024
	global_load_dwordx4 v[74:77], v214, s[4:5] offset:1024
	global_load_dwordx4 v[78:81], v214, s[6:7] offset:1024
	ds_read_b128 v[130:133], v219
	ds_read_b128 v[134:137], v220
	ds_read_b128 v[138:141], v219 offset:4608
	s_waitcnt lgkmcnt(11)
	v_mfma_f32_32x32x16_bf16 v[18:33], v[154:157], v[158:161], v[18:33]
	ds_read_b128 v[142:145], v219 offset:32
	ds_read_b128 v[146:149], v220 offset:32
	ds_read_b128 v[150:153], v219 offset:4640
	s_waitcnt lgkmcnt(13)
	v_mfma_f32_32x32x16_bf16 v[2:17], v[162:165], v[158:161], v[2:17]
	s_waitcnt lgkmcnt(11)
	v_mfma_f32_32x32x16_bf16 v[18:33], v[166:169], v[170:173], v[18:33]
	s_waitcnt lgkmcnt(10)
	v_mfma_f32_32x32x16_bf16 v[2:17], v[174:177], v[170:173], v[2:17]
	s_waitcnt lgkmcnt(0)
	s_barrier
	ds_read_b128 v[154:157], v219 offset:64
	ds_read_b128 v[158:161], v220 offset:64
	ds_read_b128 v[162:165], v219 offset:4672
	v_mfma_f32_32x32x16_bf16 v[18:33], v[130:133], v[134:137], v[18:33]
	ds_read_b128 v[166:169], v219 offset:96
	ds_read_b128 v[170:173], v220 offset:96
	ds_read_b128 v[174:177], v219 offset:4704
	v_mfma_f32_32x32x16_bf16 v[2:17], v[138:141], v[134:137], v[2:17]
	s_waitcnt vmcnt(16)
	ds_write_b128 v218, v[82:85] offset:36864
	ds_write_b128 v218, v[86:89] offset:46080
	v_mfma_f32_32x32x16_bf16 v[18:33], v[142:145], v[146:149], v[18:33]
	ds_write_b128 v223, v[90:93] offset:36864
	ds_write_b128 v223, v[94:97] offset:46080
	v_mfma_f32_32x32x16_bf16 v[2:17], v[150:153], v[146:149], v[2:17]
	global_load_dwordx4 v[82:85], v210, s[0:1] offset:1152
	global_load_dwordx4 v[86:89], v210, s[2:3] offset:1152
	global_load_dwordx4 v[90:93], v214, s[4:5] offset:1152
	global_load_dwordx4 v[94:97], v214, s[6:7] offset:1152
	ds_read_b128 v[130:133], v219 offset:18432
	ds_read_b128 v[134:137], v220 offset:18432
	ds_read_b128 v[138:141], v219 offset:23040
	s_waitcnt lgkmcnt(11)
	v_mfma_f32_32x32x16_bf16 v[18:33], v[154:157], v[158:161], v[18:33]
	ds_read_b128 v[142:145], v219 offset:18464
	ds_read_b128 v[146:149], v220 offset:18464
	ds_read_b128 v[150:153], v219 offset:23072
	s_waitcnt lgkmcnt(13)
	v_mfma_f32_32x32x16_bf16 v[2:17], v[162:165], v[158:161], v[2:17]
	s_waitcnt lgkmcnt(11)
	v_mfma_f32_32x32x16_bf16 v[18:33], v[166:169], v[170:173], v[18:33]
	s_waitcnt lgkmcnt(10)
	v_mfma_f32_32x32x16_bf16 v[2:17], v[174:177], v[170:173], v[2:17]
	s_waitcnt lgkmcnt(0)
	s_barrier
	ds_read_b128 v[154:157], v219 offset:18496
	ds_read_b128 v[158:161], v220 offset:18496
	ds_read_b128 v[162:165], v219 offset:23104
	v_mfma_f32_32x32x16_bf16 v[18:33], v[130:133], v[134:137], v[18:33]
	ds_read_b128 v[166:169], v219 offset:18528
	ds_read_b128 v[170:173], v220 offset:18528
	ds_read_b128 v[174:177], v219 offset:23136
	v_mfma_f32_32x32x16_bf16 v[2:17], v[138:141], v[134:137], v[2:17]
	s_waitcnt vmcnt(12)
	ds_write_b128 v218, v[98:101]
	ds_write_b128 v218, v[102:105] offset:9216
	v_mfma_f32_32x32x16_bf16 v[18:33], v[142:145], v[146:149], v[18:33]
	ds_write_b128 v223, v[106:109]
	ds_write_b128 v223, v[110:113] offset:9216
	v_mfma_f32_32x32x16_bf16 v[2:17], v[150:153], v[146:149], v[2:17]
	global_load_dwordx4 v[98:101], v210, s[0:1] offset:1280
	global_load_dwordx4 v[102:105], v210, s[2:3] offset:1280
	global_load_dwordx4 v[106:109], v214, s[4:5] offset:1280
	global_load_dwordx4 v[110:113], v214, s[6:7] offset:1280
	ds_read_b128 v[130:133], v219 offset:36864
	ds_read_b128 v[134:137], v220 offset:36864
	ds_read_b128 v[138:141], v219 offset:41472
	s_waitcnt lgkmcnt(11)
	v_mfma_f32_32x32x16_bf16 v[18:33], v[154:157], v[158:161], v[18:33]
	ds_read_b128 v[142:145], v219 offset:36896
	ds_read_b128 v[146:149], v220 offset:36896
	ds_read_b128 v[150:153], v219 offset:41504
	s_waitcnt lgkmcnt(13)
	v_mfma_f32_32x32x16_bf16 v[2:17], v[162:165], v[158:161], v[2:17]
	s_waitcnt lgkmcnt(11)
	v_mfma_f32_32x32x16_bf16 v[18:33], v[166:169], v[170:173], v[18:33]
	s_waitcnt lgkmcnt(10)
	v_mfma_f32_32x32x16_bf16 v[2:17], v[174:177], v[170:173], v[2:17]
	s_waitcnt lgkmcnt(0)
	s_barrier
; DI f32x16 mfma(bf16x8 a, bf16x8 b, f32x16 c) { return __builtin_amdgcn_mfma_f32_32x32x16_bf16(a, b, c, 0, 0, 0); }
; template <bool RFA, bool RFB, class LA, class LB, class EPI>
; DI void gemm_tile2s(u16* smem, int nk, LA la, LB lb, EPI epi) {
;     ...
;   auto compute = [&](int buf) __attribute__((always_inline)) {
;     const u16* Ab = As + buf * TILE_ELEMS + (wm * 64 + lr) * LDT + lh * 8;
;     const u16* Bb = Bs + buf * TILE_ELEMS + (wn * 32 + lr) * LDT + lh * 8;
; #pragma unroll
;     for (int ks = 0; ks < 4; ++ks) {
;       const bf16x8 a0 = *(const bf16x8*)(Ab + ks * 16);
;       const bf16x8 a1 = *(const bf16x8*)(Ab + 32 * LDT + ks * 16);
;       const bf16x8 b = *(const bf16x8*)(Bb + ks * 16);
;       acc[0] = mfma(a0, b, acc[0]);
;       acc[1] = mfma(a1, b, acc[1]);
;     }
;   };
;   ld(ra0, rb0, 0);
;   if (nk > 1) ld(ra1, rb1, 1);
;   stl(ra0, rb0, 0);
;   if (nk > 2) ld(ra0, rb0, 2);
;   __syncthreads();
; #pragma unroll 1
;   for (int kt = 0; kt < nk; kt += 2) {
;     compute(0);
;     if (kt + 1 < nk) { stl(ra1, rb1, 1); if (kt + 3 < nk) ld(ra1, rb1, kt + 3); }
;     __syncthreads();
;     if (kt + 1 < nk) {
;       compute(1);
;       if (kt + 2 < nk) { stl(ra0, rb0, 0); if (kt + 4 < nk) ld(ra0, rb0, kt + 4); }
;       __syncthreads();
;     }
;   }
; template <class ACC>
; DI void merge_branch(const Prm& p, u16* smem, const u16* W, const u16* X, int ld, int bi, int n0, int m0, ACC& macc) {
;     ...
;   auto epi = [&](f32x16 (&acc)[2], int wm, int wn, int lane) __attribute__((always_inline)) {
;     const int lr = lane & 31, lh = lane >> 5;
;     const int tok = m0 + wn * 32 + lr;
; #pragma unroll
;     for (int i = 0; i < 2; ++i)
; #pragma unroll
;       for (int h2 = 0; h2 < 2; ++h2) {
;         const int n = n0 + wm * 64 + i * 32 + 16 * lh + 8 * h2;
;         const u32x4 gz = *(const u32x4*)(p.zg + (size_t)tok * 4096 + bi * 1024 + n);
	ds_read_b128 v[154:157], v219 offset:36928
	ds_read_b128 v[158:161], v220 offset:36928
	ds_read_b128 v[162:165], v219 offset:41536
	v_mfma_f32_32x32x16_bf16 v[18:33], v[130:133], v[134:137], v[18:33]
	ds_read_b128 v[166:169], v219 offset:36960
	ds_read_b128 v[170:173], v220 offset:36960
	ds_read_b128 v[174:177], v219 offset:41568
	v_mfma_f32_32x32x16_bf16 v[2:17], v[138:141], v[134:137], v[2:17]
	s_waitcnt vmcnt(12)
	ds_write_b128 v218, v[114:117] offset:18432
	ds_write_b128 v218, v[118:121] offset:27648
	v_mfma_f32_32x32x16_bf16 v[18:33], v[142:145], v[146:149], v[18:33]
	ds_write_b128 v223, v[122:125] offset:18432
	ds_write_b128 v223, v[126:129] offset:27648
	v_mfma_f32_32x32x16_bf16 v[2:17], v[150:153], v[146:149], v[2:17]
	global_load_dwordx4 v[114:117], v210, s[0:1] offset:1408
	global_load_dwordx4 v[118:121], v210, s[2:3] offset:1408
	global_load_dwordx4 v[122:125], v214, s[4:5] offset:1408
	global_load_dwordx4 v[126:129], v214, s[6:7] offset:1408
	global_load_dwordx4 v[178:181], v221, s[8:9]
	global_load_dwordx4 v[182:185], v221, s[8:9] offset:16
	global_load_dwordx4 v[186:189], v221, s[8:9] offset:64
	global_load_dwordx4 v[190:193], v221, s[8:9] offset:80
	ds_read_b128 v[130:133], v219
	ds_read_b128 v[134:137], v220
	ds_read_b128 v[138:141], v219 offset:4608
	s_waitcnt lgkmcnt(11)
	v_mfma_f32_32x32x16_bf16 v[18:33], v[154:157], v[158:161], v[18:33]
	ds_read_b128 v[142:145], v219 offset:32
	ds_read_b128 v[146:149], v220 offset:32
	ds_read_b128 v[150:153], v219 offset:4640
	s_waitcnt lgkmcnt(13)
	v_mfma_f32_32x32x16_bf16 v[2:17], v[162:165], v[158:161], v[2:17]
	s_waitcnt lgkmcnt(11)
	v_mfma_f32_32x32x16_bf16 v[18:33], v[166:169], v[170:173], v[18:33]
	s_waitcnt lgkmcnt(10)
	v_mfma_f32_32x32x16_bf16 v[2:17], v[174:177], v[170:173], v[2:17]
	s_waitcnt lgkmcnt(0)
	s_barrier
	ds_read_b128 v[154:157], v219 offset:64
	ds_read_b128 v[158:161], v220 offset:64
	ds_read_b128 v[162:165], v219 offset:4672
	v_mfma_f32_32x32x16_bf16 v[18:33], v[130:133], v[134:137], v[18:33]
	ds_read_b128 v[166:169], v219 offset:96
	ds_read_b128 v[170:173], v220 offset:96
	ds_read_b128 v[174:177], v219 offset:4704
	v_mfma_f32_32x32x16_bf16 v[2:17], v[138:141], v[134:137], v[2:17]
	s_waitcnt vmcnt(16)
	ds_write_b128 v218, v[66:69] offset:36864
	ds_write_b128 v218, v[70:73] offset:46080
	v_mfma_f32_32x32x16_bf16 v[18:33], v[142:145], v[146:149], v[18:33]
	ds_write_b128 v223, v[74:77] offset:36864
	ds_write_b128 v223, v[78:81] offset:46080
	v_mfma_f32_32x32x16_bf16 v[2:17], v[150:153], v[146:149], v[2:17]
	s_mul_i32 s52, s58, 0x100
	s_add_u32 s0, s20, s52
	s_addc_u32 s1, s21, 0
	s_add_u32 s2, s0, 0x4000
	s_addc_u32 s3, s1, 0
	s_mul_i32 s52, s59, 0x100
	s_add_u32 s4, s36, s52
	s_addc_u32 s5, s37, 0
	s_add_u32 s6, s4, 0x4000
	s_addc_u32 s7, s5, 0
	global_load_dwordx4 v[66:69], v211, s[0:1]
	global_load_dwordx4 v[70:73], v211, s[2:3]
	global_load_dwordx4 v[74:77], v215, s[4:5]
	global_load_dwordx4 v[78:81], v215, s[6:7]
	ds_read_b128 v[130:133], v219 offset:18432
	ds_read_b128 v[134:137], v220 offset:18432
	ds_read_b128 v[138:141], v219 offset:23040
	s_waitcnt lgkmcnt(11)
	v_mfma_f32_32x32x16_bf16 v[18:33], v[154:157], v[158:161], v[18:33]
	ds_read_b128 v[142:145], v219 offset:18464
	ds_read_b128 v[146:149], v220 offset:18464
	ds_read_b128 v[150:153], v219 offset:23072
	s_waitcnt lgkmcnt(13)
	v_mfma_f32_32x32x16_bf16 v[2:17], v[162:165], v[158:161], v[2:17]
	s_waitcnt lgkmcnt(11)
	v_mfma_f32_32x32x16_bf16 v[18:33], v[166:169], v[170:173], v[18:33]
	s_waitcnt lgkmcnt(10)
	v_mfma_f32_32x32x16_bf16 v[2:17], v[174:177], v[170:173], v[2:17]
	s_waitcnt lgkmcnt(0)
	s_barrier
	ds_read_b128 v[154:157], v219 offset:18496
	ds_read_b128 v[158:161], v220 offset:18496
	ds_read_b128 v[162:165], v219 offset:23104
	v_mfma_f32_32x32x16_bf16 v[18:33], v[130:133], v[134:137], v[18:33]
	ds_read_b128 v[166:169], v219 offset:18528
	ds_read_b128 v[170:173], v220 offset:18528
	ds_read_b128 v[174:177], v219 offset:23136
	v_mfma_f32_32x32x16_bf16 v[2:17], v[138:141], v[134:137], v[2:17]
	s_waitcnt vmcnt(16)
	ds_write_b128 v218, v[82:85]
	ds_write_b128 v218, v[86:89] offset:9216
	v_mfma_f32_32x32x16_bf16 v[18:33], v[142:145], v[146:149], v[18:33]
	ds_write_b128 v223, v[90:93]
	ds_write_b128 v223, v[94:97] offset:9216
	v_mfma_f32_32x32x16_bf16 v[2:17], v[150:153], v[146:149], v[2:17]
	global_load_dwordx4 v[82:85], v211, s[0:1] offset:128
	global_load_dwordx4 v[86:89], v211, s[2:3] offset:128
	global_load_dwordx4 v[90:93], v215, s[4:5] offset:128
	global_load_dwordx4 v[94:97], v215, s[6:7] offset:128
	global_load_dwordx4 v[194:197], v221, s[8:9] offset:2048
	global_load_dwordx4 v[198:201], v221, s[8:9] offset:2064
	global_load_dwordx4 v[202:205], v221, s[8:9] offset:2112
	global_load_dwordx4 v[206:209], v221, s[8:9] offset:2128
	ds_read_b128 v[130:133], v219 offset:36864
	ds_read_b128 v[134:137], v220 offset:36864
	ds_read_b128 v[138:141], v219 offset:41472
	s_waitcnt lgkmcnt(11)
	v_mfma_f32_32x32x16_bf16 v[18:33], v[154:157], v[158:161], v[18:33]
	ds_read_b128 v[142:145], v219 offset:36896
	ds_read_b128 v[146:149], v220 offset:36896
	ds_read_b128 v[150:153], v219 offset:41504
	s_waitcnt lgkmcnt(13)
	v_mfma_f32_32x32x16_bf16 v[2:17], v[162:165], v[158:161], v[2:17]
	s_waitcnt lgkmcnt(11)
	v_mfma_f32_32x32x16_bf16 v[18:33], v[166:169], v[170:173], v[18:33]
	s_waitcnt lgkmcnt(10)
	v_mfma_f32_32x32x16_bf16 v[2:17], v[174:177], v[170:173], v[2:17]
	s_waitcnt lgkmcnt(0)
	s_barrier
; DI f32x16 mfma(bf16x8 a, bf16x8 b, f32x16 c) { return __builtin_amdgcn_mfma_f32_32x32x16_bf16(a, b, c, 0, 0, 0); }
; template <bool RFA, bool RFB, class LA, class LB, class EPI>
; DI void gemm_tile2s(u16* smem, int nk, LA la, LB lb, EPI epi) {
;     ...
;   auto compute = [&](int buf) __attribute__((always_inline)) {
;     const u16* Ab = As + buf * TILE_ELEMS + (wm * 64 + lr) * LDT + lh * 8;
;     const u16* Bb = Bs + buf * TILE_ELEMS + (wn * 32 + lr) * LDT + lh * 8;
; #pragma unroll
;     for (int ks = 0; ks < 4; ++ks) {
;       const bf16x8 a0 = *(const bf16x8*)(Ab + ks * 16);
;       const bf16x8 a1 = *(const bf16x8*)(Ab + 32 * LDT + ks * 16);
;       const bf16x8 b = *(const bf16x8*)(Bb + ks * 16);
;       acc[0] = mfma(a0, b, acc[0]);
;       acc[1] = mfma(a1, b, acc[1]);
;     }
;   };
;   ld(ra0, rb0, 0);
;   if (nk > 1) ld(ra1, rb1, 1);
;   stl(ra0, rb0, 0);
;   if (nk > 2) ld(ra0, rb0, 2);
;   __syncthreads();
; #pragma unroll 1
;   for (int kt = 0; kt < nk; kt += 2) {
;     compute(0);
;     if (kt + 1 < nk) { stl(ra1, rb1, 1); if (kt + 3 < nk) ld(ra1, rb1, kt + 3); }
;     __syncthreads();
;     if (kt + 1 < nk) {
;       compute(1);
;       if (kt + 2 < nk) { stl(ra0, rb0, 0); if (kt + 4 < nk) ld(ra0, rb0, kt + 4); }
;       __syncthreads();
;     }
;   }
	ds_read_b128 v[154:157], v219 offset:36928
	ds_read_b128 v[158:161], v220 offset:36928
	ds_read_b128 v[162:165], v219 offset:41536
	v_mfma_f32_32x32x16_bf16 v[18:33], v[130:133], v[134:137], v[18:33]
	ds_read_b128 v[166:169], v219 offset:36960
	ds_read_b128 v[170:173], v220 offset:36960
	ds_read_b128 v[174:177], v219 offset:41568
	v_mfma_f32_32x32x16_bf16 v[2:17], v[138:141], v[134:137], v[2:17]
	s_waitcnt vmcnt(20)
	ds_write_b128 v218, v[98:101] offset:18432
	ds_write_b128 v218, v[102:105] offset:27648
	v_mfma_f32_32x32x16_bf16 v[18:33], v[142:145], v[146:149], v[18:33]
	ds_write_b128 v223, v[106:109] offset:18432
	ds_write_b128 v223, v[110:113] offset:27648
	v_mfma_f32_32x32x16_bf16 v[2:17], v[150:153], v[146:149], v[2:17]
	s_mul_i32 s52, s58, 0x300
	s_add_u32 s0, s22, s52
	s_addc_u32 s1, s23, 0
	s_add_u32 s2, s0, 0xc000
	s_addc_u32 s3, s1, 0
	s_mul_i32 s52, s59, 0x300
	s_add_u32 s4, s38, s52
	s_addc_u32 s5, s39, 0
	s_add_u32 s6, s4, 0xc000
	s_addc_u32 s7, s5, 0
	global_load_dwordx4 v[98:101], v212, s[0:1]
	global_load_dwordx4 v[102:105], v212, s[2:3]
	global_load_dwordx4 v[106:109], v216, s[4:5]
	global_load_dwordx4 v[110:113], v216, s[6:7]
	ds_read_b128 v[130:133], v219
	ds_read_b128 v[134:137], v220
	ds_read_b128 v[138:141], v219 offset:4608
	s_waitcnt lgkmcnt(11)
	v_mfma_f32_32x32x16_bf16 v[18:33], v[154:157], v[158:161], v[18:33]
	ds_read_b128 v[142:145], v219 offset:32
	ds_read_b128 v[146:149], v220 offset:32
	ds_read_b128 v[150:153], v219 offset:4640
	s_waitcnt lgkmcnt(13)
	v_mfma_f32_32x32x16_bf16 v[2:17], v[162:165], v[158:161], v[2:17]
	s_waitcnt lgkmcnt(11)
	v_mfma_f32_32x32x16_bf16 v[18:33], v[166:169], v[170:173], v[18:33]
	s_waitcnt lgkmcnt(10)
	v_mfma_f32_32x32x16_bf16 v[2:17], v[174:177], v[170:173], v[2:17]
	s_waitcnt lgkmcnt(0)
	s_barrier
	ds_read_b128 v[154:157], v219 offset:64
	ds_read_b128 v[158:161], v220 offset:64
	ds_read_b128 v[162:165], v219 offset:4672
	v_mfma_f32_32x32x16_bf16 v[18:33], v[130:133], v[134:137], v[18:33]
	ds_read_b128 v[166:169], v219 offset:96
	ds_read_b128 v[170:173], v220 offset:96
	ds_read_b128 v[174:177], v219 offset:4704
	v_mfma_f32_32x32x16_bf16 v[2:17], v[138:141], v[134:137], v[2:17]
	s_waitcnt vmcnt(20)
	ds_write_b128 v218, v[114:117] offset:36864
	ds_write_b128 v218, v[118:121] offset:46080
	v_mfma_f32_32x32x16_bf16 v[18:33], v[142:145], v[146:149], v[18:33]
	ds_write_b128 v223, v[122:125] offset:36864
	ds_write_b128 v223, v[126:129] offset:46080
	v_mfma_f32_32x32x16_bf16 v[2:17], v[150:153], v[146:149], v[2:17]
	global_load_dwordx4 v[114:117], v212, s[0:1] offset:128
	global_load_dwordx4 v[118:121], v212, s[2:3] offset:128
	global_load_dwordx4 v[122:125], v216, s[4:5] offset:128
	global_load_dwordx4 v[126:129], v216, s[6:7] offset:128
	ds_read_b128 v[130:133], v219 offset:18432
	ds_read_b128 v[134:137], v220 offset:18432
	ds_read_b128 v[138:141], v219 offset:23040
	s_waitcnt lgkmcnt(11)
	v_mfma_f32_32x32x16_bf16 v[18:33], v[154:157], v[158:161], v[18:33]
	ds_read_b128 v[142:145], v219 offset:18464
	ds_read_b128 v[146:149], v220 offset:18464
	ds_read_b128 v[150:153], v219 offset:23072
	s_waitcnt lgkmcnt(13)
	v_mfma_f32_32x32x16_bf16 v[2:17], v[162:165], v[158:161], v[2:17]
	s_waitcnt lgkmcnt(11)
	v_mfma_f32_32x32x16_bf16 v[18:33], v[166:169], v[170:173], v[18:33]
	s_waitcnt lgkmcnt(10)
	v_mfma_f32_32x32x16_bf16 v[2:17], v[174:177], v[170:173], v[2:17]
	s_waitcnt lgkmcnt(0)
	s_barrier
	ds_read_b128 v[154:157], v219 offset:18496
	ds_read_b128 v[158:161], v220 offset:18496
	ds_read_b128 v[162:165], v219 offset:23104
	v_mfma_f32_32x32x16_bf16 v[18:33], v[130:133], v[134:137], v[18:33]
	ds_read_b128 v[166:169], v219 offset:18528
	ds_read_b128 v[170:173], v220 offset:18528
	ds_read_b128 v[174:177], v219 offset:23136
	v_mfma_f32_32x32x16_bf16 v[2:17], v[138:141], v[134:137], v[2:17]
	s_waitcnt vmcnt(16)
	ds_write_b128 v218, v[66:69]
	ds_write_b128 v218, v[70:73] offset:9216
	v_mfma_f32_32x32x16_bf16 v[18:33], v[142:145], v[146:149], v[18:33]
	ds_write_b128 v223, v[74:77]
	ds_write_b128 v223, v[78:81] offset:9216
	v_mfma_f32_32x32x16_bf16 v[2:17], v[150:153], v[146:149], v[2:17]
	global_load_dwordx4 v[66:69], v212, s[0:1] offset:256
	global_load_dwordx4 v[70:73], v212, s[2:3] offset:256
	global_load_dwordx4 v[74:77], v216, s[4:5] offset:256
	global_load_dwordx4 v[78:81], v216, s[6:7] offset:256
	ds_read_b128 v[130:133], v219 offset:36864
	ds_read_b128 v[134:137], v220 offset:36864
	ds_read_b128 v[138:141], v219 offset:41472
	s_waitcnt lgkmcnt(11)
	v_mfma_f32_32x32x16_bf16 v[18:33], v[154:157], v[158:161], v[18:33]
	ds_read_b128 v[142:145], v219 offset:36896
	ds_read_b128 v[146:149], v220 offset:36896
	ds_read_b128 v[150:153], v219 offset:41504
	s_waitcnt lgkmcnt(13)
	v_mfma_f32_32x32x16_bf16 v[2:17], v[162:165], v[158:161], v[2:17]
	s_waitcnt lgkmcnt(11)
	v_mfma_f32_32x32x16_bf16 v[18:33], v[166:169], v[170:173], v[18:33]
	s_waitcnt lgkmcnt(10)
	v_mfma_f32_32x32x16_bf16 v[2:17], v[174:177], v[170:173], v[2:17]
	s_waitcnt lgkmcnt(0)
	s_barrier
; DI float bflo(unsigned w) { return __uint_as_float(w << 16); }
; DI float bfhi(unsigned w) { return __uint_as_float(w & 0xffff0000u); }
; DI f32x16 mfma(bf16x8 a, bf16x8 b, f32x16 c) { return __builtin_amdgcn_mfma_f32_32x32x16_bf16(a, b, c, 0, 0, 0); }
; template <bool RFA, bool RFB, class LA, class LB, class EPI>
; DI void gemm_tile2s(u16* smem, int nk, LA la, LB lb, EPI epi) {
;     ...
;   auto compute = [&](int buf) __attribute__((always_inline)) {
;     const u16* Ab = As + buf * TILE_ELEMS + (wm * 64 + lr) * LDT + lh * 8;
;     const u16* Bb = Bs + buf * TILE_ELEMS + (wn * 32 + lr) * LDT + lh * 8;
; #pragma unroll
;     for (int ks = 0; ks < 4; ++ks) {
;       const bf16x8 a0 = *(const bf16x8*)(Ab + ks * 16);
;       const bf16x8 a1 = *(const bf16x8*)(Ab + 32 * LDT + ks * 16);
;       const bf16x8 b = *(const bf16x8*)(Bb + ks * 16);
;       acc[0] = mfma(a0, b, acc[0]);
;       acc[1] = mfma(a1, b, acc[1]);
;     }
;   };
;   ld(ra0, rb0, 0);
;   if (nk > 1) ld(ra1, rb1, 1);
;   stl(ra0, rb0, 0);
;   if (nk > 2) ld(ra0, rb0, 2);
;   __syncthreads();
; #pragma unroll 1
;   for (int kt = 0; kt < nk; kt += 2) {
;     compute(0);
;     if (kt + 1 < nk) { stl(ra1, rb1, 1); if (kt + 3 < nk) ld(ra1, rb1, kt + 3); }
;     __syncthreads();
;     if (kt + 1 < nk) {
;       compute(1);
;       if (kt + 2 < nk) { stl(ra0, rb0, 0); if (kt + 4 < nk) ld(ra0, rb0, kt + 4); }
;       __syncthreads();
;     }
;   }
; template <class ACC>
; DI void merge_branch(const Prm& p, u16* smem, const u16* W, const u16* X, int ld, int bi, int n0, int m0, ACC& macc) {
;     ...
;   auto epi = [&](f32x16 (&acc)[2], int wm, int wn, int lane) __attribute__((always_inline)) {
;     const int lr = lane & 31, lh = lane >> 5;
;     const int tok = m0 + wn * 32 + lr;
; #pragma unroll
;     for (int i = 0; i < 2; ++i)
; #pragma unroll
;       for (int h2 = 0; h2 < 2; ++h2) {
;         const int n = n0 + wm * 64 + i * 32 + 16 * lh + 8 * h2;
;         const u32x4 gz = *(const u32x4*)(p.zg + (size_t)tok * 4096 + bi * 1024 + n);
; #pragma unroll
;         for (int e = 0; e < 4; ++e) {
;           macc[i][8 * h2 + 2 * e] += bflo(gz[e]) * acc[i][8 * h2 + 2 * e];
;           macc[i][8 * h2 + 2 * e + 1] += bfhi(gz[e]) * acc[i][8 * h2 + 2 * e + 1];
;         }
;       }
;   };
	ds_read_b128 v[154:157], v219 offset:36928
	ds_read_b128 v[158:161], v220 offset:36928
	ds_read_b128 v[162:165], v219 offset:41536
	v_mfma_f32_32x32x16_bf16 v[18:33], v[130:133], v[134:137], v[18:33]
	ds_read_b128 v[166:169], v219 offset:36960
	ds_read_b128 v[170:173], v220 offset:36960
	ds_read_b128 v[174:177], v219 offset:41568
	v_mfma_f32_32x32x16_bf16 v[2:17], v[138:141], v[134:137], v[2:17]
	s_waitcnt vmcnt(16)
	ds_write_b128 v218, v[82:85] offset:18432
	ds_write_b128 v218, v[86:89] offset:27648
	v_mfma_f32_32x32x16_bf16 v[18:33], v[142:145], v[146:149], v[18:33]
	ds_write_b128 v223, v[90:93] offset:18432
	ds_write_b128 v223, v[94:97] offset:27648
	v_mfma_f32_32x32x16_bf16 v[2:17], v[150:153], v[146:149], v[2:17]
	global_load_dwordx4 v[82:85], v212, s[0:1] offset:384
	global_load_dwordx4 v[86:89], v212, s[2:3] offset:384
	global_load_dwordx4 v[90:93], v216, s[4:5] offset:384
	global_load_dwordx4 v[94:97], v216, s[6:7] offset:384
	ds_read_b128 v[130:133], v219
	ds_read_b128 v[134:137], v220
	ds_read_b128 v[138:141], v219 offset:4608
	s_waitcnt lgkmcnt(11)
	v_mfma_f32_32x32x16_bf16 v[18:33], v[154:157], v[158:161], v[18:33]
	ds_read_b128 v[142:145], v219 offset:32
	ds_read_b128 v[146:149], v220 offset:32
	ds_read_b128 v[150:153], v219 offset:4640
	s_waitcnt lgkmcnt(13)
	v_mfma_f32_32x32x16_bf16 v[2:17], v[162:165], v[158:161], v[2:17]
	s_waitcnt lgkmcnt(11)
	v_mfma_f32_32x32x16_bf16 v[18:33], v[166:169], v[170:173], v[18:33]
	s_waitcnt lgkmcnt(10)
	v_mfma_f32_32x32x16_bf16 v[2:17], v[174:177], v[170:173], v[2:17]
	s_waitcnt vmcnt(28)
	s_nop 15
	v_lshlrev_b32_e32 v226, 16, v178
	v_and_b32_e32 v227, 0xffff0000, v178
	v_pk_mul_f32 v[34:35], v[226:227], v[18:19]
	v_lshlrev_b32_e32 v228, 16, v179
	v_and_b32_e32 v229, 0xffff0000, v179
	v_pk_mul_f32 v[36:37], v[228:229], v[20:21]
	v_lshlrev_b32_e32 v234, 16, v180
	v_and_b32_e32 v235, 0xffff0000, v180
	v_pk_mul_f32 v[38:39], v[234:235], v[22:23]
	v_lshlrev_b32_e32 v236, 16, v181
	v_and_b32_e32 v237, 0xffff0000, v181
	v_pk_mul_f32 v[40:41], v[236:237], v[24:25]
	v_lshlrev_b32_e32 v226, 16, v182
	v_and_b32_e32 v227, 0xffff0000, v182
	v_pk_mul_f32 v[42:43], v[226:227], v[26:27]
	v_lshlrev_b32_e32 v228, 16, v183
	v_and_b32_e32 v229, 0xffff0000, v183
	v_pk_mul_f32 v[44:45], v[228:229], v[28:29]
	v_lshlrev_b32_e32 v234, 16, v184
	v_and_b32_e32 v235, 0xffff0000, v184
	v_pk_mul_f32 v[46:47], v[234:235], v[30:31]
	v_lshlrev_b32_e32 v236, 16, v185
	v_and_b32_e32 v237, 0xffff0000, v185
	v_pk_mul_f32 v[48:49], v[236:237], v[32:33]
	v_lshlrev_b32_e32 v226, 16, v186
	v_and_b32_e32 v227, 0xffff0000, v186
	v_pk_mul_f32 v[50:51], v[226:227], v[2:3]
	v_lshlrev_b32_e32 v228, 16, v187
	v_and_b32_e32 v229, 0xffff0000, v187
	v_pk_mul_f32 v[52:53], v[228:229], v[4:5]
	v_lshlrev_b32_e32 v234, 16, v188
	v_and_b32_e32 v235, 0xffff0000, v188
	v_pk_mul_f32 v[54:55], v[234:235], v[6:7]
	v_lshlrev_b32_e32 v236, 16, v189
	v_and_b32_e32 v237, 0xffff0000, v189
	v_pk_mul_f32 v[56:57], v[236:237], v[8:9]
	v_lshlrev_b32_e32 v226, 16, v190
	v_and_b32_e32 v227, 0xffff0000, v190
	v_pk_mul_f32 v[58:59], v[226:227], v[10:11]
	v_lshlrev_b32_e32 v228, 16, v191
	v_and_b32_e32 v229, 0xffff0000, v191
	v_pk_mul_f32 v[60:61], v[228:229], v[12:13]
	v_lshlrev_b32_e32 v234, 16, v192
	v_and_b32_e32 v235, 0xffff0000, v192
	v_pk_mul_f32 v[62:63], v[234:235], v[14:15]
	v_lshlrev_b32_e32 v236, 16, v193
	v_and_b32_e32 v237, 0xffff0000, v193
	v_pk_mul_f32 v[64:65], v[236:237], v[16:17]
	s_waitcnt lgkmcnt(0)
	s_barrier
	ds_read_b128 v[154:157], v219 offset:64
	ds_read_b128 v[158:161], v220 offset:64
	ds_read_b128 v[162:165], v219 offset:4672
	v_mfma_f32_32x32x16_bf16 v[18:33], v[130:133], v[134:137], 0
	ds_read_b128 v[166:169], v219 offset:96
	ds_read_b128 v[170:173], v220 offset:96
	ds_read_b128 v[174:177], v219 offset:4704
	v_mfma_f32_32x32x16_bf16 v[2:17], v[138:141], v[134:137], 0
	s_waitcnt vmcnt(12)
	ds_write_b128 v218, v[98:101] offset:36864
	ds_write_b128 v218, v[102:105] offset:46080
	v_mfma_f32_32x32x16_bf16 v[18:33], v[142:145], v[146:149], v[18:33]
	ds_write_b128 v223, v[106:109] offset:36864
	ds_write_b128 v223, v[110:113] offset:46080
	v_mfma_f32_32x32x16_bf16 v[2:17], v[150:153], v[146:149], v[2:17]
	global_load_dwordx4 v[98:101], v212, s[0:1] offset:512
	global_load_dwordx4 v[102:105], v212, s[2:3] offset:512
	global_load_dwordx4 v[106:109], v216, s[4:5] offset:512
	global_load_dwordx4 v[110:113], v216, s[6:7] offset:512
	global_load_dwordx4 v[178:181], v221, s[10:11]
	global_load_dwordx4 v[182:185], v221, s[10:11] offset:16
	global_load_dwordx4 v[186:189], v221, s[10:11] offset:64
	global_load_dwordx4 v[190:193], v221, s[10:11] offset:80
	ds_read_b128 v[130:133], v219 offset:18432
	ds_read_b128 v[134:137], v220 offset:18432
	ds_read_b128 v[138:141], v219 offset:23040
	s_waitcnt lgkmcnt(11)
	v_mfma_f32_32x32x16_bf16 v[18:33], v[154:157], v[158:161], v[18:33]
	ds_read_b128 v[142:145], v219 offset:18464
	ds_read_b128 v[146:149], v220 offset:18464
	ds_read_b128 v[150:153], v219 offset:23072
	s_waitcnt lgkmcnt(13)
	v_mfma_f32_32x32x16_bf16 v[2:17], v[162:165], v[158:161], v[2:17]
	s_waitcnt lgkmcnt(11)
	v_mfma_f32_32x32x16_bf16 v[18:33], v[166:169], v[170:173], v[18:33]
	s_waitcnt lgkmcnt(10)
	v_mfma_f32_32x32x16_bf16 v[2:17], v[174:177], v[170:173], v[2:17]
	s_waitcnt lgkmcnt(0)
	s_barrier
; DI float bflo(unsigned w) { return __uint_as_float(w << 16); }
; DI float bfhi(unsigned w) { return __uint_as_float(w & 0xffff0000u); }
; template <bool RFA, bool RFB, class LA, class LB, class EPI>
; DI void gemm_tile2s(u16* smem, int nk, LA la, LB lb, EPI epi) {
;     ...
;   auto compute = [&](int buf) __attribute__((always_inline)) {
;     const u16* Ab = As + buf * TILE_ELEMS + (wm * 64 + lr) * LDT + lh * 8;
;     const u16* Bb = Bs + buf * TILE_ELEMS + (wn * 32 + lr) * LDT + lh * 8;
; #pragma unroll
;     for (int ks = 0; ks < 4; ++ks) {
;       const bf16x8 a0 = *(const bf16x8*)(Ab + ks * 16);
;       const bf16x8 a1 = *(const bf16x8*)(Ab + 32 * LDT + ks * 16);
;       const bf16x8 b = *(const bf16x8*)(Bb + ks * 16);
;       acc[0] = mfma(a0, b, acc[0]);
;       acc[1] = mfma(a1, b, acc[1]);
;     }
;   };
;   ld(ra0, rb0, 0);
;   if (nk > 1) ld(ra1, rb1, 1);
;   stl(ra0, rb0, 0);
;   if (nk > 2) ld(ra0, rb0, 2);
;   __syncthreads();
; #pragma unroll 1
;   for (int kt = 0; kt < nk; kt += 2) {
;     compute(0);
;     if (kt + 1 < nk) { stl(ra1, rb1, 1); if (kt + 3 < nk) ld(ra1, rb1, kt + 3); }
;     __syncthreads();
;     if (kt + 1 < nk) {
;       compute(1);
;       if (kt + 2 < nk) { stl(ra0, rb0, 0); if (kt + 4 < nk) ld(ra0, rb0, kt + 4); }
;       __syncthreads();
;     }
;   }
; template <class ACC>
; DI void merge_branch(const Prm& p, u16* smem, const u16* W, const u16* X, int ld, int bi, int n0, int m0, ACC& macc) {
;     ...
;   auto epi = [&](f32x16 (&acc)[2], int wm, int wn, int lane) __attribute__((always_inline)) {
;     const int lr = lane & 31, lh = lane >> 5;
;     const int tok = m0 + wn * 32 + lr;
; #pragma unroll
;     for (int i = 0; i < 2; ++i)
; #pragma unroll
;       for (int h2 = 0; h2 < 2; ++h2) {
;         const int n = n0 + wm * 64 + i * 32 + 16 * lh + 8 * h2;
;         const u32x4 gz = *(const u32x4*)(p.zg + (size_t)tok * 4096 + bi * 1024 + n);
; #pragma unroll
;         for (int e = 0; e < 4; ++e) {
;           macc[i][8 * h2 + 2 * e] += bflo(gz[e]) * acc[i][8 * h2 + 2 * e];
;           macc[i][8 * h2 + 2 * e + 1] += bfhi(gz[e]) * acc[i][8 * h2 + 2 * e + 1];
;         }
;       }
;   };
; DI void phase_merge(const Prm& p, u16* smem, int l, int& base) {
;     ...
;     merge_branch(p, smem, p.PdT + (size_t)l * 1024 * 256, p.od, 256, 3, n0, m0, macc);
	ds_read_b128 v[154:157], v219 offset:18496
	ds_read_b128 v[158:161], v220 offset:18496
	ds_read_b128 v[162:165], v219 offset:23104
	v_mfma_f32_32x32x16_bf16 v[18:33], v[130:133], v[134:137], v[18:33]
	ds_read_b128 v[166:169], v219 offset:18528
	ds_read_b128 v[170:173], v220 offset:18528
	ds_read_b128 v[174:177], v219 offset:23136
	v_mfma_f32_32x32x16_bf16 v[2:17], v[138:141], v[134:137], v[2:17]
	s_waitcnt vmcnt(16)
	ds_write_b128 v218, v[114:117]
	ds_write_b128 v218, v[118:121] offset:9216
	v_mfma_f32_32x32x16_bf16 v[18:33], v[142:145], v[146:149], v[18:33]
	ds_write_b128 v223, v[122:125]
	ds_write_b128 v223, v[126:129] offset:9216
	v_mfma_f32_32x32x16_bf16 v[2:17], v[150:153], v[146:149], v[2:17]
	global_load_dwordx4 v[114:117], v212, s[0:1] offset:640
	global_load_dwordx4 v[118:121], v212, s[2:3] offset:640
	global_load_dwordx4 v[122:125], v216, s[4:5] offset:640
	global_load_dwordx4 v[126:129], v216, s[6:7] offset:640
	ds_read_b128 v[130:133], v219 offset:36864
	ds_read_b128 v[134:137], v220 offset:36864
	ds_read_b128 v[138:141], v219 offset:41472
	s_waitcnt lgkmcnt(11)
	v_mfma_f32_32x32x16_bf16 v[18:33], v[154:157], v[158:161], v[18:33]
	ds_read_b128 v[142:145], v219 offset:36896
	ds_read_b128 v[146:149], v220 offset:36896
	ds_read_b128 v[150:153], v219 offset:41504
	s_waitcnt lgkmcnt(13)
	v_mfma_f32_32x32x16_bf16 v[2:17], v[162:165], v[158:161], v[2:17]
	s_waitcnt lgkmcnt(11)
	v_mfma_f32_32x32x16_bf16 v[18:33], v[166:169], v[170:173], v[18:33]
	s_waitcnt lgkmcnt(10)
	v_mfma_f32_32x32x16_bf16 v[2:17], v[174:177], v[170:173], v[2:17]
	s_waitcnt vmcnt(28)
	s_nop 15
	v_lshlrev_b32_e32 v226, 16, v194
	v_and_b32_e32 v227, 0xffff0000, v194
	v_pk_fma_f32 v[34:35], v[226:227], v[18:19], v[34:35]
	v_lshlrev_b32_e32 v228, 16, v195
	v_and_b32_e32 v229, 0xffff0000, v195
	v_pk_fma_f32 v[36:37], v[228:229], v[20:21], v[36:37]
	v_lshlrev_b32_e32 v234, 16, v196
	v_and_b32_e32 v235, 0xffff0000, v196
	v_pk_fma_f32 v[38:39], v[234:235], v[22:23], v[38:39]
	v_lshlrev_b32_e32 v236, 16, v197
	v_and_b32_e32 v237, 0xffff0000, v197
	v_pk_fma_f32 v[40:41], v[236:237], v[24:25], v[40:41]
	v_lshlrev_b32_e32 v226, 16, v198
	v_and_b32_e32 v227, 0xffff0000, v198
	v_pk_fma_f32 v[42:43], v[226:227], v[26:27], v[42:43]
	v_lshlrev_b32_e32 v228, 16, v199
	v_and_b32_e32 v229, 0xffff0000, v199
	v_pk_fma_f32 v[44:45], v[228:229], v[28:29], v[44:45]
	v_lshlrev_b32_e32 v234, 16, v200
	v_and_b32_e32 v235, 0xffff0000, v200
	v_pk_fma_f32 v[46:47], v[234:235], v[30:31], v[46:47]
	v_lshlrev_b32_e32 v236, 16, v201
	v_and_b32_e32 v237, 0xffff0000, v201
	v_pk_fma_f32 v[48:49], v[236:237], v[32:33], v[48:49]
	v_lshlrev_b32_e32 v226, 16, v202
	v_and_b32_e32 v227, 0xffff0000, v202
	v_pk_fma_f32 v[50:51], v[226:227], v[2:3], v[50:51]
	v_lshlrev_b32_e32 v228, 16, v203
	v_and_b32_e32 v229, 0xffff0000, v203
	v_pk_fma_f32 v[52:53], v[228:229], v[4:5], v[52:53]
	v_lshlrev_b32_e32 v234, 16, v204
	v_and_b32_e32 v235, 0xffff0000, v204
	v_pk_fma_f32 v[54:55], v[234:235], v[6:7], v[54:55]
	v_lshlrev_b32_e32 v236, 16, v205
	v_and_b32_e32 v237, 0xffff0000, v205
	v_pk_fma_f32 v[56:57], v[236:237], v[8:9], v[56:57]
	v_lshlrev_b32_e32 v226, 16, v206
	v_and_b32_e32 v227, 0xffff0000, v206
	v_pk_fma_f32 v[58:59], v[226:227], v[10:11], v[58:59]
	v_lshlrev_b32_e32 v228, 16, v207
	v_and_b32_e32 v229, 0xffff0000, v207
	v_pk_fma_f32 v[60:61], v[228:229], v[12:13], v[60:61]
	v_lshlrev_b32_e32 v234, 16, v208
	v_and_b32_e32 v235, 0xffff0000, v208
	v_pk_fma_f32 v[62:63], v[234:235], v[14:15], v[62:63]
	v_lshlrev_b32_e32 v236, 16, v209
	v_and_b32_e32 v237, 0xffff0000, v209
	v_pk_fma_f32 v[64:65], v[236:237], v[16:17], v[64:65]
	s_waitcnt lgkmcnt(0)
	s_barrier
	ds_read_b128 v[154:157], v219 offset:36928
	ds_read_b128 v[158:161], v220 offset:36928
	ds_read_b128 v[162:165], v219 offset:41536
	v_mfma_f32_32x32x16_bf16 v[18:33], v[130:133], v[134:137], 0
	ds_read_b128 v[166:169], v219 offset:36960
	ds_read_b128 v[170:173], v220 offset:36960
	ds_read_b128 v[174:177], v219 offset:41568
	v_mfma_f32_32x32x16_bf16 v[2:17], v[138:141], v[134:137], 0
	s_waitcnt vmcnt(16)
	ds_write_b128 v218, v[66:69] offset:18432
	ds_write_b128 v218, v[70:73] offset:27648
	v_mfma_f32_32x32x16_bf16 v[18:33], v[142:145], v[146:149], v[18:33]
	ds_write_b128 v223, v[74:77] offset:18432
	ds_write_b128 v223, v[78:81] offset:27648
	v_mfma_f32_32x32x16_bf16 v[2:17], v[150:153], v[146:149], v[2:17]
	s_mul_i32 s52, s58, 0x200
	s_add_u32 s0, s44, s52
	s_addc_u32 s1, s45, 0
	s_add_u32 s2, s0, 0x8000
	s_addc_u32 s3, s1, 0
	s_mul_i32 s52, s59, 0x200
	s_add_u32 s4, s40, s52
	s_addc_u32 s5, s41, 0
	s_add_u32 s6, s4, 0x8000
	s_addc_u32 s7, s5, 0
	global_load_dwordx4 v[66:69], v213, s[0:1]
	global_load_dwordx4 v[70:73], v213, s[2:3]
	global_load_dwordx4 v[74:77], v217, s[4:5]
	global_load_dwordx4 v[78:81], v217, s[6:7]
	global_load_dwordx4 v[194:197], v221, s[10:11] offset:2048
	global_load_dwordx4 v[198:201], v221, s[10:11] offset:2064
	global_load_dwordx4 v[202:205], v221, s[10:11] offset:2112
	global_load_dwordx4 v[206:209], v221, s[10:11] offset:2128
	ds_read_b128 v[130:133], v219
	ds_read_b128 v[134:137], v220
	ds_read_b128 v[138:141], v219 offset:4608
	s_waitcnt lgkmcnt(11)
	v_mfma_f32_32x32x16_bf16 v[18:33], v[154:157], v[158:161], v[18:33]
	ds_read_b128 v[142:145], v219 offset:32
	ds_read_b128 v[146:149], v220 offset:32
	ds_read_b128 v[150:153], v219 offset:4640
	s_waitcnt lgkmcnt(13)
	v_mfma_f32_32x32x16_bf16 v[2:17], v[162:165], v[158:161], v[2:17]
	s_waitcnt lgkmcnt(11)
	v_mfma_f32_32x32x16_bf16 v[18:33], v[166:169], v[170:173], v[18:33]
	s_waitcnt lgkmcnt(10)
	v_mfma_f32_32x32x16_bf16 v[2:17], v[174:177], v[170:173], v[2:17]
	s_waitcnt lgkmcnt(0)
	s_barrier
; DI f32x16 mfma(bf16x8 a, bf16x8 b, f32x16 c) { return __builtin_amdgcn_mfma_f32_32x32x16_bf16(a, b, c, 0, 0, 0); }
; template <bool RFA, bool RFB, class LA, class LB, class EPI>
; DI void gemm_tile2s(u16* smem, int nk, LA la, LB lb, EPI epi) {
;     ...
;   auto compute = [&](int buf) __attribute__((always_inline)) {
;     const u16* Ab = As + buf * TILE_ELEMS + (wm * 64 + lr) * LDT + lh * 8;
;     const u16* Bb = Bs + buf * TILE_ELEMS + (wn * 32 + lr) * LDT + lh * 8;
; #pragma unroll
;     for (int ks = 0; ks < 4; ++ks) {
;       const bf16x8 a0 = *(const bf16x8*)(Ab + ks * 16);
;       const bf16x8 a1 = *(const bf16x8*)(Ab + 32 * LDT + ks * 16);
;       const bf16x8 b = *(const bf16x8*)(Bb + ks * 16);
;       acc[0] = mfma(a0, b, acc[0]);
;       acc[1] = mfma(a1, b, acc[1]);
;     }
;   };
;   ld(ra0, rb0, 0);
;   if (nk > 1) ld(ra1, rb1, 1);
;   stl(ra0, rb0, 0);
;   if (nk > 2) ld(ra0, rb0, 2);
;   __syncthreads();
; #pragma unroll 1
;   for (int kt = 0; kt < nk; kt += 2) {
;     compute(0);
;     if (kt + 1 < nk) { stl(ra1, rb1, 1); if (kt + 3 < nk) ld(ra1, rb1, kt + 3); }
;     __syncthreads();
;     if (kt + 1 < nk) {
;       compute(1);
;       if (kt + 2 < nk) { stl(ra0, rb0, 0); if (kt + 4 < nk) ld(ra0, rb0, kt + 4); }
;       __syncthreads();
;     }
;   }
	ds_read_b128 v[154:157], v219 offset:64
	ds_read_b128 v[158:161], v220 offset:64
	ds_read_b128 v[162:165], v219 offset:4672
	v_mfma_f32_32x32x16_bf16 v[18:33], v[130:133], v[134:137], v[18:33]
	ds_read_b128 v[166:169], v219 offset:96
	ds_read_b128 v[170:173], v220 offset:96
	ds_read_b128 v[174:177], v219 offset:4704
	v_mfma_f32_32x32x16_bf16 v[2:17], v[138:141], v[134:137], v[2:17]
	s_waitcnt vmcnt(20)
	ds_write_b128 v218, v[82:85] offset:36864
	ds_write_b128 v218, v[86:89] offset:46080
	v_mfma_f32_32x32x16_bf16 v[18:33], v[142:145], v[146:149], v[18:33]
	ds_write_b128 v223, v[90:93] offset:36864
	ds_write_b128 v223, v[94:97] offset:46080
	v_mfma_f32_32x32x16_bf16 v[2:17], v[150:153], v[146:149], v[2:17]
	global_load_dwordx4 v[82:85], v213, s[0:1] offset:128
	global_load_dwordx4 v[86:89], v213, s[2:3] offset:128
	global_load_dwordx4 v[90:93], v217, s[4:5] offset:128
	global_load_dwordx4 v[94:97], v217, s[6:7] offset:128
	ds_read_b128 v[130:133], v219 offset:18432
	ds_read_b128 v[134:137], v220 offset:18432
	ds_read_b128 v[138:141], v219 offset:23040
	s_waitcnt lgkmcnt(11)
	v_mfma_f32_32x32x16_bf16 v[18:33], v[154:157], v[158:161], v[18:33]
	ds_read_b128 v[142:145], v219 offset:18464
	ds_read_b128 v[146:149], v220 offset:18464
	ds_read_b128 v[150:153], v219 offset:23072
	s_waitcnt lgkmcnt(13)
	v_mfma_f32_32x32x16_bf16 v[2:17], v[162:165], v[158:161], v[2:17]
	s_waitcnt lgkmcnt(11)
	v_mfma_f32_32x32x16_bf16 v[18:33], v[166:169], v[170:173], v[18:33]
	s_waitcnt lgkmcnt(10)
	v_mfma_f32_32x32x16_bf16 v[2:17], v[174:177], v[170:173], v[2:17]
	s_waitcnt lgkmcnt(0)
	s_barrier
	ds_read_b128 v[154:157], v219 offset:18496
	ds_read_b128 v[158:161], v220 offset:18496
	ds_read_b128 v[162:165], v219 offset:23104
	v_mfma_f32_32x32x16_bf16 v[18:33], v[130:133], v[134:137], v[18:33]
	ds_read_b128 v[166:169], v219 offset:18528
	ds_read_b128 v[170:173], v220 offset:18528
	ds_read_b128 v[174:177], v219 offset:23136
	v_mfma_f32_32x32x16_bf16 v[2:17], v[138:141], v[134:137], v[2:17]
	s_waitcnt vmcnt(20)
	ds_write_b128 v218, v[98:101]
	ds_write_b128 v218, v[102:105] offset:9216
	v_mfma_f32_32x32x16_bf16 v[18:33], v[142:145], v[146:149], v[18:33]
	ds_write_b128 v223, v[106:109]
	ds_write_b128 v223, v[110:113] offset:9216
	v_mfma_f32_32x32x16_bf16 v[2:17], v[150:153], v[146:149], v[2:17]
	global_load_dwordx4 v[98:101], v213, s[0:1] offset:256
	global_load_dwordx4 v[102:105], v213, s[2:3] offset:256
	global_load_dwordx4 v[106:109], v217, s[4:5] offset:256
	global_load_dwordx4 v[110:113], v217, s[6:7] offset:256
	ds_read_b128 v[130:133], v219 offset:36864
	ds_read_b128 v[134:137], v220 offset:36864
	ds_read_b128 v[138:141], v219 offset:41472
	s_waitcnt lgkmcnt(11)
	v_mfma_f32_32x32x16_bf16 v[18:33], v[154:157], v[158:161], v[18:33]
	ds_read_b128 v[142:145], v219 offset:36896
	ds_read_b128 v[146:149], v220 offset:36896
	ds_read_b128 v[150:153], v219 offset:41504
	s_waitcnt lgkmcnt(13)
	v_mfma_f32_32x32x16_bf16 v[2:17], v[162:165], v[158:161], v[2:17]
	s_waitcnt lgkmcnt(11)
	v_mfma_f32_32x32x16_bf16 v[18:33], v[166:169], v[170:173], v[18:33]
	s_waitcnt lgkmcnt(10)
	v_mfma_f32_32x32x16_bf16 v[2:17], v[174:177], v[170:173], v[2:17]
	s_waitcnt lgkmcnt(0)
	s_barrier
	ds_read_b128 v[154:157], v219 offset:36928
	ds_read_b128 v[158:161], v220 offset:36928
	ds_read_b128 v[162:165], v219 offset:41536
	v_mfma_f32_32x32x16_bf16 v[18:33], v[130:133], v[134:137], v[18:33]
	ds_read_b128 v[166:169], v219 offset:36960
	ds_read_b128 v[170:173], v220 offset:36960
	ds_read_b128 v[174:177], v219 offset:41568
	v_mfma_f32_32x32x16_bf16 v[2:17], v[138:141], v[134:137], v[2:17]
	s_waitcnt vmcnt(16)
	ds_write_b128 v218, v[114:117] offset:18432
	ds_write_b128 v218, v[118:121] offset:27648
	v_mfma_f32_32x32x16_bf16 v[18:33], v[142:145], v[146:149], v[18:33]
	ds_write_b128 v223, v[122:125] offset:18432
	ds_write_b128 v223, v[126:129] offset:27648
	v_mfma_f32_32x32x16_bf16 v[2:17], v[150:153], v[146:149], v[2:17]
	global_load_dwordx4 v[114:117], v213, s[0:1] offset:384
	global_load_dwordx4 v[118:121], v213, s[2:3] offset:384
	global_load_dwordx4 v[122:125], v217, s[4:5] offset:384
	global_load_dwordx4 v[126:129], v217, s[6:7] offset:384
	ds_read_b128 v[130:133], v219
	ds_read_b128 v[134:137], v220
	ds_read_b128 v[138:141], v219 offset:4608
	s_waitcnt lgkmcnt(11)
	v_mfma_f32_32x32x16_bf16 v[18:33], v[154:157], v[158:161], v[18:33]
	ds_read_b128 v[142:145], v219 offset:32
	ds_read_b128 v[146:149], v220 offset:32
	ds_read_b128 v[150:153], v219 offset:4640
	s_waitcnt lgkmcnt(13)
	v_mfma_f32_32x32x16_bf16 v[2:17], v[162:165], v[158:161], v[2:17]
	s_waitcnt lgkmcnt(11)
	v_mfma_f32_32x32x16_bf16 v[18:33], v[166:169], v[170:173], v[18:33]
	s_waitcnt lgkmcnt(10)
	v_mfma_f32_32x32x16_bf16 v[2:17], v[174:177], v[170:173], v[2:17]
	s_waitcnt lgkmcnt(0)
	s_barrier
; DI float bflo(unsigned w) { return __uint_as_float(w << 16); }
; DI float bfhi(unsigned w) { return __uint_as_float(w & 0xffff0000u); }
; DI f32x16 mfma(bf16x8 a, bf16x8 b, f32x16 c) { return __builtin_amdgcn_mfma_f32_32x32x16_bf16(a, b, c, 0, 0, 0); }
; #define TASK_LOOP(t, nt, base) for (int t = (int)((blockIdx.x + gridDim.x - ((unsigned)(base) % gridDim.x)) % gridDim.x); t < (nt); t += gridDim.x)
; template <bool RFA, bool RFB, class LA, class LB, class EPI>
; DI void gemm_tile2s(u16* smem, int nk, LA la, LB lb, EPI epi) {
;     ...
;   auto compute = [&](int buf) __attribute__((always_inline)) {
;     const u16* Ab = As + buf * TILE_ELEMS + (wm * 64 + lr) * LDT + lh * 8;
;     const u16* Bb = Bs + buf * TILE_ELEMS + (wn * 32 + lr) * LDT + lh * 8;
; #pragma unroll
;     for (int ks = 0; ks < 4; ++ks) {
;       const bf16x8 a0 = *(const bf16x8*)(Ab + ks * 16);
;       const bf16x8 a1 = *(const bf16x8*)(Ab + 32 * LDT + ks * 16);
;       const bf16x8 b = *(const bf16x8*)(Bb + ks * 16);
;       acc[0] = mfma(a0, b, acc[0]);
;       acc[1] = mfma(a1, b, acc[1]);
;     }
;   };
;   ld(ra0, rb0, 0);
;   if (nk > 1) ld(ra1, rb1, 1);
;   stl(ra0, rb0, 0);
;   if (nk > 2) ld(ra0, rb0, 2);
;   __syncthreads();
; #pragma unroll 1
;   for (int kt = 0; kt < nk; kt += 2) {
;     compute(0);
;     if (kt + 1 < nk) { stl(ra1, rb1, 1); if (kt + 3 < nk) ld(ra1, rb1, kt + 3); }
;     __syncthreads();
;     if (kt + 1 < nk) {
;       compute(1);
;       if (kt + 2 < nk) { stl(ra0, rb0, 0); if (kt + 4 < nk) ld(ra0, rb0, kt + 4); }
;       __syncthreads();
;     }
;   }
; template <class ACC>
; DI void merge_branch(const Prm& p, u16* smem, const u16* W, const u16* X, int ld, int bi, int n0, int m0, ACC& macc) {
;     ...
;         const u32x4 gz = *(const u32x4*)(p.zg + (size_t)tok * 4096 + bi * 1024 + n);
; #pragma unroll
;         for (int e = 0; e < 4; ++e) {
;           macc[i][8 * h2 + 2 * e] += bflo(gz[e]) * acc[i][8 * h2 + 2 * e];
;           macc[i][8 * h2 + 2 * e + 1] += bfhi(gz[e]) * acc[i][8 * h2 + 2 * e + 1];
;         }
; DI void phase_merge(const Prm& p, u16* smem, int l, int& base) {
;   TASK_LOOP(t, 8 * 128, base) {
;     const int tn = t & 7, tm = t >> 3, n0 = tn * 128, m0 = tm * 128;
	ds_read_b128 v[154:157], v219 offset:64
	ds_read_b128 v[158:161], v220 offset:64
	ds_read_b128 v[162:165], v219 offset:4672
	v_mfma_f32_32x32x16_bf16 v[18:33], v[130:133], v[134:137], v[18:33]
	ds_read_b128 v[166:169], v219 offset:96
	ds_read_b128 v[170:173], v220 offset:96
	ds_read_b128 v[174:177], v219 offset:4704
	v_mfma_f32_32x32x16_bf16 v[2:17], v[138:141], v[134:137], v[2:17]
	s_waitcnt vmcnt(16)
	ds_write_b128 v218, v[66:69] offset:36864
	ds_write_b128 v218, v[70:73] offset:46080
	v_mfma_f32_32x32x16_bf16 v[18:33], v[142:145], v[146:149], v[18:33]
	ds_write_b128 v223, v[74:77] offset:36864
	ds_write_b128 v223, v[78:81] offset:46080
	v_mfma_f32_32x32x16_bf16 v[2:17], v[150:153], v[146:149], v[2:17]
	s_add_i32 s50, s31, s30
	s_cmpk_lt_i32 s50, 0x400
	s_cselect_b32 s50, s50, s31
	s_and_b32 s52, s50, 7
	s_lshl_b32 s52, s52, 4
	s_lshr_b32 s53, s50, 9
	s_lshl_b32 s53, s53, 3
	s_or_b32 s52, s52, s53
	s_bfe_u32 s53, s50, 0x30005
	s_or_b32 s52, s52, s53
	s_lshl_b32 s61, s52, 7
	s_bfe_u32 s52, s50, 0x10008
	s_lshl_b32 s52, s52, 2
	s_bfe_u32 s53, s50, 0x20003
	s_or_b32 s52, s52, s53
	s_lshl_b32 s60, s52, 7
	s_mul_i32 s52, s60, 0x600
	s_add_u32 s0, s16, s52
	s_addc_u32 s1, s17, 0
	s_add_u32 s2, s0, 0x18000
	s_addc_u32 s3, s1, 0
	s_mul_i32 s52, s61, 0x600
	s_add_u32 s4, s14, s52
	s_addc_u32 s5, s15, 0
	s_add_u32 s6, s4, 0x18000
	s_addc_u32 s7, s5, 0
	global_load_dwordx4 v[66:69], v210, s[0:1]
	global_load_dwordx4 v[70:73], v210, s[2:3]
	global_load_dwordx4 v[74:77], v214, s[4:5]
	global_load_dwordx4 v[78:81], v214, s[6:7]
	ds_read_b128 v[130:133], v219 offset:18432
	ds_read_b128 v[134:137], v220 offset:18432
	ds_read_b128 v[138:141], v219 offset:23040
	s_waitcnt lgkmcnt(11)
	v_mfma_f32_32x32x16_bf16 v[18:33], v[154:157], v[158:161], v[18:33]
	ds_read_b128 v[142:145], v219 offset:18464
	ds_read_b128 v[146:149], v220 offset:18464
	ds_read_b128 v[150:153], v219 offset:23072
	s_waitcnt lgkmcnt(13)
	v_mfma_f32_32x32x16_bf16 v[2:17], v[162:165], v[158:161], v[2:17]
	s_waitcnt lgkmcnt(11)
	v_mfma_f32_32x32x16_bf16 v[18:33], v[166:169], v[170:173], v[18:33]
	s_waitcnt lgkmcnt(10)
	v_mfma_f32_32x32x16_bf16 v[2:17], v[174:177], v[170:173], v[2:17]
	s_waitcnt lgkmcnt(0)
	s_barrier
	ds_read_b128 v[154:157], v219 offset:18496
	ds_read_b128 v[158:161], v220 offset:18496
	ds_read_b128 v[162:165], v219 offset:23104
	v_mfma_f32_32x32x16_bf16 v[18:33], v[130:133], v[134:137], v[18:33]
	ds_read_b128 v[166:169], v219 offset:18528
	ds_read_b128 v[170:173], v220 offset:18528
	ds_read_b128 v[174:177], v219 offset:23136
	v_mfma_f32_32x32x16_bf16 v[2:17], v[138:141], v[134:137], v[2:17]
	s_waitcnt vmcnt(12)
	ds_write_b128 v218, v[82:85]
	ds_write_b128 v218, v[86:89] offset:9216
	v_mfma_f32_32x32x16_bf16 v[18:33], v[142:145], v[146:149], v[18:33]
	ds_write_b128 v223, v[90:93]
	ds_write_b128 v223, v[94:97] offset:9216
	v_mfma_f32_32x32x16_bf16 v[2:17], v[150:153], v[146:149], v[2:17]
	global_load_dwordx4 v[82:85], v210, s[0:1] offset:128
	global_load_dwordx4 v[86:89], v210, s[2:3] offset:128
	global_load_dwordx4 v[90:93], v214, s[4:5] offset:128
	global_load_dwordx4 v[94:97], v214, s[6:7] offset:128
	ds_read_b128 v[130:133], v219 offset:36864
	ds_read_b128 v[134:137], v220 offset:36864
	ds_read_b128 v[138:141], v219 offset:41472
	s_waitcnt lgkmcnt(11)
	v_mfma_f32_32x32x16_bf16 v[18:33], v[154:157], v[158:161], v[18:33]
	ds_read_b128 v[142:145], v219 offset:36896
	ds_read_b128 v[146:149], v220 offset:36896
	ds_read_b128 v[150:153], v219 offset:41504
	s_waitcnt lgkmcnt(13)
	v_mfma_f32_32x32x16_bf16 v[2:17], v[162:165], v[158:161], v[2:17]
	s_waitcnt lgkmcnt(11)
	v_mfma_f32_32x32x16_bf16 v[18:33], v[166:169], v[170:173], v[18:33]
	s_waitcnt lgkmcnt(10)
	v_mfma_f32_32x32x16_bf16 v[2:17], v[174:177], v[170:173], v[2:17]
	s_waitcnt vmcnt(32)
	s_nop 15
	v_lshlrev_b32_e32 v226, 16, v178
	v_and_b32_e32 v227, 0xffff0000, v178
	v_pk_fma_f32 v[34:35], v[226:227], v[18:19], v[34:35]
	v_lshlrev_b32_e32 v228, 16, v179
	v_and_b32_e32 v229, 0xffff0000, v179
	v_pk_fma_f32 v[36:37], v[228:229], v[20:21], v[36:37]
	v_lshlrev_b32_e32 v234, 16, v180
	v_and_b32_e32 v235, 0xffff0000, v180
	v_pk_fma_f32 v[38:39], v[234:235], v[22:23], v[38:39]
	v_lshlrev_b32_e32 v236, 16, v181
	v_and_b32_e32 v237, 0xffff0000, v181
	v_pk_fma_f32 v[40:41], v[236:237], v[24:25], v[40:41]
	v_lshlrev_b32_e32 v226, 16, v182
	v_and_b32_e32 v227, 0xffff0000, v182
	v_pk_fma_f32 v[42:43], v[226:227], v[26:27], v[42:43]
	v_lshlrev_b32_e32 v228, 16, v183
	v_and_b32_e32 v229, 0xffff0000, v183
	v_pk_fma_f32 v[44:45], v[228:229], v[28:29], v[44:45]
	v_lshlrev_b32_e32 v234, 16, v184
	v_and_b32_e32 v235, 0xffff0000, v184
	v_pk_fma_f32 v[46:47], v[234:235], v[30:31], v[46:47]
	v_lshlrev_b32_e32 v236, 16, v185
	v_and_b32_e32 v237, 0xffff0000, v185
	v_pk_fma_f32 v[48:49], v[236:237], v[32:33], v[48:49]
	v_lshlrev_b32_e32 v226, 16, v186
	v_and_b32_e32 v227, 0xffff0000, v186
	v_pk_fma_f32 v[50:51], v[226:227], v[2:3], v[50:51]
	v_lshlrev_b32_e32 v228, 16, v187
	v_and_b32_e32 v229, 0xffff0000, v187
	v_pk_fma_f32 v[52:53], v[228:229], v[4:5], v[52:53]
	v_lshlrev_b32_e32 v234, 16, v188
	v_and_b32_e32 v235, 0xffff0000, v188
	v_pk_fma_f32 v[54:55], v[234:235], v[6:7], v[54:55]
	v_lshlrev_b32_e32 v236, 16, v189
	v_and_b32_e32 v237, 0xffff0000, v189
	v_pk_fma_f32 v[56:57], v[236:237], v[8:9], v[56:57]
	v_lshlrev_b32_e32 v226, 16, v190
	v_and_b32_e32 v227, 0xffff0000, v190
	v_pk_fma_f32 v[58:59], v[226:227], v[10:11], v[58:59]
	v_lshlrev_b32_e32 v228, 16, v191
	v_and_b32_e32 v229, 0xffff0000, v191
	v_pk_fma_f32 v[60:61], v[228:229], v[12:13], v[60:61]
	v_lshlrev_b32_e32 v234, 16, v192
	v_and_b32_e32 v235, 0xffff0000, v192
	v_pk_fma_f32 v[62:63], v[234:235], v[14:15], v[62:63]
	v_lshlrev_b32_e32 v236, 16, v193
	v_and_b32_e32 v237, 0xffff0000, v193
	v_pk_fma_f32 v[64:65], v[236:237], v[16:17], v[64:65]
	s_waitcnt lgkmcnt(0)
	s_barrier
; DI f32x16 mfma(bf16x8 a, bf16x8 b, f32x16 c) { return __builtin_amdgcn_mfma_f32_32x32x16_bf16(a, b, c, 0, 0, 0); }
; template <bool RFA, bool RFB, class LA, class LB, class EPI>
; DI void gemm_tile2s(u16* smem, int nk, LA la, LB lb, EPI epi) {
;     ...
;   auto compute = [&](int buf) __attribute__((always_inline)) {
;     const u16* Ab = As + buf * TILE_ELEMS + (wm * 64 + lr) * LDT + lh * 8;
;     const u16* Bb = Bs + buf * TILE_ELEMS + (wn * 32 + lr) * LDT + lh * 8;
; #pragma unroll
;     for (int ks = 0; ks < 4; ++ks) {
;       const bf16x8 a0 = *(const bf16x8*)(Ab + ks * 16);
;       const bf16x8 a1 = *(const bf16x8*)(Ab + 32 * LDT + ks * 16);
;       const bf16x8 b = *(const bf16x8*)(Bb + ks * 16);
;       acc[0] = mfma(a0, b, acc[0]);
;       acc[1] = mfma(a1, b, acc[1]);
;     }
;   };
;   ld(ra0, rb0, 0);
;   if (nk > 1) ld(ra1, rb1, 1);
;   stl(ra0, rb0, 0);
;   if (nk > 2) ld(ra0, rb0, 2);
;   __syncthreads();
; #pragma unroll 1
;   for (int kt = 0; kt < nk; kt += 2) {
;     compute(0);
;     if (kt + 1 < nk) { stl(ra1, rb1, 1); if (kt + 3 < nk) ld(ra1, rb1, kt + 3); }
;     __syncthreads();
;     if (kt + 1 < nk) {
;       compute(1);
;       if (kt + 2 < nk) { stl(ra0, rb0, 0); if (kt + 4 < nk) ld(ra0, rb0, kt + 4); }
;       __syncthreads();
;     }
;   }
	ds_read_b128 v[154:157], v219 offset:36928
	ds_read_b128 v[158:161], v220 offset:36928
	ds_read_b128 v[162:165], v219 offset:41536
	v_mfma_f32_32x32x16_bf16 v[18:33], v[130:133], v[134:137], 0
	ds_read_b128 v[166:169], v219 offset:36960
	ds_read_b128 v[170:173], v220 offset:36960
	ds_read_b128 v[174:177], v219 offset:41568
	v_mfma_f32_32x32x16_bf16 v[2:17], v[138:141], v[134:137], 0
	s_waitcnt vmcnt(12)
	ds_write_b128 v218, v[98:101] offset:18432
	ds_write_b128 v218, v[102:105] offset:27648
	v_mfma_f32_32x32x16_bf16 v[18:33], v[142:145], v[146:149], v[18:33]
	ds_write_b128 v223, v[106:109] offset:18432
	ds_write_b128 v223, v[110:113] offset:27648
	v_mfma_f32_32x32x16_bf16 v[2:17], v[150:153], v[146:149], v[2:17]
	global_load_dwordx4 v[98:101], v210, s[0:1] offset:256
	global_load_dwordx4 v[102:105], v210, s[2:3] offset:256
	global_load_dwordx4 v[106:109], v214, s[4:5] offset:256
	global_load_dwordx4 v[110:113], v214, s[6:7] offset:256
	ds_read_b128 v[130:133], v219
	ds_read_b128 v[134:137], v220
	ds_read_b128 v[138:141], v219 offset:4608
	s_waitcnt lgkmcnt(11)
	v_mfma_f32_32x32x16_bf16 v[18:33], v[154:157], v[158:161], v[18:33]
	ds_read_b128 v[142:145], v219 offset:32
	ds_read_b128 v[146:149], v220 offset:32
	ds_read_b128 v[150:153], v219 offset:4640
	s_waitcnt lgkmcnt(13)
	v_mfma_f32_32x32x16_bf16 v[2:17], v[162:165], v[158:161], v[2:17]
	s_waitcnt lgkmcnt(11)
	v_mfma_f32_32x32x16_bf16 v[18:33], v[166:169], v[170:173], v[18:33]
	s_waitcnt lgkmcnt(10)
	v_mfma_f32_32x32x16_bf16 v[2:17], v[174:177], v[170:173], v[2:17]
	s_waitcnt lgkmcnt(0)
	s_barrier
	ds_read_b128 v[154:157], v219 offset:64
	ds_read_b128 v[158:161], v220 offset:64
	ds_read_b128 v[162:165], v219 offset:4672
	v_mfma_f32_32x32x16_bf16 v[18:33], v[130:133], v[134:137], v[18:33]
	ds_read_b128 v[166:169], v219 offset:96
	ds_read_b128 v[170:173], v220 offset:96
	ds_read_b128 v[174:177], v219 offset:4704
	v_mfma_f32_32x32x16_bf16 v[2:17], v[138:141], v[134:137], v[2:17]
	s_waitcnt vmcnt(12)
	ds_write_b128 v218, v[114:117] offset:36864
	ds_write_b128 v218, v[118:121] offset:46080
	v_mfma_f32_32x32x16_bf16 v[18:33], v[142:145], v[146:149], v[18:33]
	ds_write_b128 v223, v[122:125] offset:36864
	ds_write_b128 v223, v[126:129] offset:46080
	v_mfma_f32_32x32x16_bf16 v[2:17], v[150:153], v[146:149], v[2:17]
	global_load_dwordx4 v[114:117], v210, s[0:1] offset:384
	global_load_dwordx4 v[118:121], v210, s[2:3] offset:384
	global_load_dwordx4 v[122:125], v214, s[4:5] offset:384
	global_load_dwordx4 v[126:129], v214, s[6:7] offset:384
	ds_read_b128 v[130:133], v219 offset:18432
	ds_read_b128 v[134:137], v220 offset:18432
	ds_read_b128 v[138:141], v219 offset:23040
	s_waitcnt lgkmcnt(11)
	v_mfma_f32_32x32x16_bf16 v[18:33], v[154:157], v[158:161], v[18:33]
	ds_read_b128 v[142:145], v219 offset:18464
	ds_read_b128 v[146:149], v220 offset:18464
	ds_read_b128 v[150:153], v219 offset:23072
	s_waitcnt lgkmcnt(13)
	v_mfma_f32_32x32x16_bf16 v[2:17], v[162:165], v[158:161], v[2:17]
	s_waitcnt lgkmcnt(11)
	v_mfma_f32_32x32x16_bf16 v[18:33], v[166:169], v[170:173], v[18:33]
	s_waitcnt lgkmcnt(10)
	v_mfma_f32_32x32x16_bf16 v[2:17], v[174:177], v[170:173], v[2:17]
	s_waitcnt lgkmcnt(0)
	s_barrier
	ds_read_b128 v[154:157], v219 offset:18496
	ds_read_b128 v[158:161], v220 offset:18496
	ds_read_b128 v[162:165], v219 offset:23104
	v_mfma_f32_32x32x16_bf16 v[18:33], v[130:133], v[134:137], v[18:33]
	ds_read_b128 v[166:169], v219 offset:18528
	ds_read_b128 v[170:173], v220 offset:18528
	ds_read_b128 v[174:177], v219 offset:23136
	v_mfma_f32_32x32x16_bf16 v[2:17], v[138:141], v[134:137], v[2:17]
	s_waitcnt vmcnt(12)
	ds_write_b128 v218, v[66:69]
	ds_write_b128 v218, v[70:73] offset:9216
	v_mfma_f32_32x32x16_bf16 v[18:33], v[142:145], v[146:149], v[18:33]
	ds_write_b128 v223, v[74:77]
	ds_write_b128 v223, v[78:81] offset:9216
	v_mfma_f32_32x32x16_bf16 v[2:17], v[150:153], v[146:149], v[2:17]
	global_load_dwordx4 v[66:69], v210, s[0:1] offset:512
	global_load_dwordx4 v[70:73], v210, s[2:3] offset:512
	global_load_dwordx4 v[74:77], v214, s[4:5] offset:512
	global_load_dwordx4 v[78:81], v214, s[6:7] offset:512
	ds_read_b128 v[130:133], v219 offset:36864
	ds_read_b128 v[134:137], v220 offset:36864
	ds_read_b128 v[138:141], v219 offset:41472
	s_waitcnt lgkmcnt(11)
	v_mfma_f32_32x32x16_bf16 v[18:33], v[154:157], v[158:161], v[18:33]
	ds_read_b128 v[142:145], v219 offset:36896
	ds_read_b128 v[146:149], v220 offset:36896
	ds_read_b128 v[150:153], v219 offset:41504
	s_waitcnt lgkmcnt(13)
	v_mfma_f32_32x32x16_bf16 v[2:17], v[162:165], v[158:161], v[2:17]
	s_waitcnt lgkmcnt(11)
	v_mfma_f32_32x32x16_bf16 v[18:33], v[166:169], v[170:173], v[18:33]
	s_waitcnt lgkmcnt(10)
	v_mfma_f32_32x32x16_bf16 v[2:17], v[174:177], v[170:173], v[2:17]
	s_waitcnt lgkmcnt(0)
	s_barrier
; DI float bflo(unsigned w) { return __uint_as_float(w << 16); }
; DI float bfhi(unsigned w) { return __uint_as_float(w & 0xffff0000u); }
; DI int tidx() { int t = threadIdx.x; asm volatile("" : "+v"(t)); return t; }
; template <class ACC>
; DI void merge_branch(const Prm& p, u16* smem, const u16* W, const u16* X, int ld, int bi, int n0, int m0, ACC& macc) {
;     ...
;   auto epi = [&](f32x16 (&acc)[2], int wm, int wn, int lane) __attribute__((always_inline)) {
;     const int lr = lane & 31, lh = lane >> 5;
;     const int tok = m0 + wn * 32 + lr;
; #pragma unroll
;     for (int i = 0; i < 2; ++i)
; #pragma unroll
;       for (int h2 = 0; h2 < 2; ++h2) {
;         const int n = n0 + wm * 64 + i * 32 + 16 * lh + 8 * h2;
;         const u32x4 gz = *(const u32x4*)(p.zg + (size_t)tok * 4096 + bi * 1024 + n);
; #pragma unroll
;         for (int e = 0; e < 4; ++e) {
;           macc[i][8 * h2 + 2 * e] += bflo(gz[e]) * acc[i][8 * h2 + 2 * e];
;           macc[i][8 * h2 + 2 * e + 1] += bfhi(gz[e]) * acc[i][8 * h2 + 2 * e + 1];
;         }
;       }
;   };
; DI void phase_merge(const Prm& p, u16* smem, int l, int& base) {
;     ...
;     const int tid2 = tidx(), lane = tid2 & 63, wave = tid2 >> 6, wm = wave >> 2, wn = wave & 3, lr = lane & 31, lh = lane >> 5;
;     const int tok = m0 + wn * 32 + lr;
; #pragma unroll
;     for (int i = 0; i < 2; ++i)
; #pragma unroll
;       for (int h2 = 0; h2 < 2; ++h2) {
;         u32x4 o;
; #pragma unroll
;         for (int e = 0; e < 4; ++e) o[e] = pack2(macc[i][8 * h2 + 2 * e], macc[i][8 * h2 + 2 * e + 1]);
;         *(u32x4*)(p.hbuf + (size_t)tok * 1024 + n0 + wm * 64 + i * 32 + 16 * lh + 8 * h2) = o;
;       }
;   }
	ds_read_b128 v[154:157], v219 offset:36928
	ds_read_b128 v[158:161], v220 offset:36928
	ds_read_b128 v[162:165], v219 offset:41536
	v_mfma_f32_32x32x16_bf16 v[18:33], v[130:133], v[134:137], v[18:33]
	ds_read_b128 v[166:169], v219 offset:36960
	ds_read_b128 v[170:173], v220 offset:36960
	ds_read_b128 v[174:177], v219 offset:41568
	v_mfma_f32_32x32x16_bf16 v[2:17], v[138:141], v[134:137], v[2:17]
	s_waitcnt vmcnt(12)
	ds_write_b128 v218, v[82:85] offset:18432
	ds_write_b128 v218, v[86:89] offset:27648
	v_mfma_f32_32x32x16_bf16 v[18:33], v[142:145], v[146:149], v[18:33]
	ds_write_b128 v223, v[90:93] offset:18432
	ds_write_b128 v223, v[94:97] offset:27648
	v_mfma_f32_32x32x16_bf16 v[2:17], v[150:153], v[146:149], v[2:17]
	global_load_dwordx4 v[82:85], v210, s[0:1] offset:640
	global_load_dwordx4 v[86:89], v210, s[2:3] offset:640
	global_load_dwordx4 v[90:93], v214, s[4:5] offset:640
	global_load_dwordx4 v[94:97], v214, s[6:7] offset:640
	ds_read_b128 v[130:133], v219
	ds_read_b128 v[134:137], v220
	ds_read_b128 v[138:141], v219 offset:4608
	s_waitcnt lgkmcnt(11)
	v_mfma_f32_32x32x16_bf16 v[18:33], v[154:157], v[158:161], v[18:33]
	ds_read_b128 v[142:145], v219 offset:32
	ds_read_b128 v[146:149], v220 offset:32
	ds_read_b128 v[150:153], v219 offset:4640
	s_waitcnt lgkmcnt(13)
	v_mfma_f32_32x32x16_bf16 v[2:17], v[162:165], v[158:161], v[2:17]
	s_waitcnt lgkmcnt(11)
	v_mfma_f32_32x32x16_bf16 v[18:33], v[166:169], v[170:173], v[18:33]
	s_waitcnt lgkmcnt(10)
	v_mfma_f32_32x32x16_bf16 v[2:17], v[174:177], v[170:173], v[2:17]
	s_waitcnt vmcnt(36)
	s_nop 15
	v_lshlrev_b32_e32 v226, 16, v194
	v_and_b32_e32 v227, 0xffff0000, v194
	v_pk_fma_f32 v[34:35], v[226:227], v[18:19], v[34:35]
	v_lshlrev_b32_e32 v228, 16, v195
	v_and_b32_e32 v229, 0xffff0000, v195
	v_pk_fma_f32 v[36:37], v[228:229], v[20:21], v[36:37]
	v_lshlrev_b32_e32 v234, 16, v196
	v_and_b32_e32 v235, 0xffff0000, v196
	v_pk_fma_f32 v[38:39], v[234:235], v[22:23], v[38:39]
	v_lshlrev_b32_e32 v236, 16, v197
	v_and_b32_e32 v237, 0xffff0000, v197
	v_pk_fma_f32 v[40:41], v[236:237], v[24:25], v[40:41]
	v_lshlrev_b32_e32 v226, 16, v198
	v_and_b32_e32 v227, 0xffff0000, v198
	v_pk_fma_f32 v[42:43], v[226:227], v[26:27], v[42:43]
	v_lshlrev_b32_e32 v228, 16, v199
	v_and_b32_e32 v229, 0xffff0000, v199
	v_pk_fma_f32 v[44:45], v[228:229], v[28:29], v[44:45]
	v_lshlrev_b32_e32 v234, 16, v200
	v_and_b32_e32 v235, 0xffff0000, v200
	v_pk_fma_f32 v[46:47], v[234:235], v[30:31], v[46:47]
	v_lshlrev_b32_e32 v236, 16, v201
	v_and_b32_e32 v237, 0xffff0000, v201
	v_pk_fma_f32 v[48:49], v[236:237], v[32:33], v[48:49]
	v_lshlrev_b32_e32 v226, 16, v202
	v_and_b32_e32 v227, 0xffff0000, v202
	v_pk_fma_f32 v[50:51], v[226:227], v[2:3], v[50:51]
	v_lshlrev_b32_e32 v228, 16, v203
	v_and_b32_e32 v229, 0xffff0000, v203
	v_pk_fma_f32 v[52:53], v[228:229], v[4:5], v[52:53]
	v_lshlrev_b32_e32 v234, 16, v204
	v_and_b32_e32 v235, 0xffff0000, v204
	v_pk_fma_f32 v[54:55], v[234:235], v[6:7], v[54:55]
	v_lshlrev_b32_e32 v236, 16, v205
	v_and_b32_e32 v237, 0xffff0000, v205
	v_pk_fma_f32 v[56:57], v[236:237], v[8:9], v[56:57]
	v_lshlrev_b32_e32 v226, 16, v206
	v_and_b32_e32 v227, 0xffff0000, v206
	v_pk_fma_f32 v[58:59], v[226:227], v[10:11], v[58:59]
	v_lshlrev_b32_e32 v228, 16, v207
	v_and_b32_e32 v229, 0xffff0000, v207
	v_pk_fma_f32 v[60:61], v[228:229], v[12:13], v[60:61]
	v_lshlrev_b32_e32 v234, 16, v208
	v_and_b32_e32 v235, 0xffff0000, v208
	v_pk_fma_f32 v[62:63], v[234:235], v[14:15], v[62:63]
	v_lshlrev_b32_e32 v236, 16, v209
	v_and_b32_e32 v237, 0xffff0000, v209
	v_pk_fma_f32 v[64:65], v[236:237], v[16:17], v[64:65]
	v_cvt_pk_bf16_f32 v178, v34, v35
	v_cvt_pk_bf16_f32 v179, v36, v37
	v_cvt_pk_bf16_f32 v180, v38, v39
	v_cvt_pk_bf16_f32 v181, v40, v41
	v_cvt_pk_bf16_f32 v182, v42, v43
	v_cvt_pk_bf16_f32 v183, v44, v45
	v_cvt_pk_bf16_f32 v184, v46, v47
	v_cvt_pk_bf16_f32 v185, v48, v49
	v_cvt_pk_bf16_f32 v186, v50, v51
	v_cvt_pk_bf16_f32 v187, v52, v53
	v_cvt_pk_bf16_f32 v188, v54, v55
	v_cvt_pk_bf16_f32 v189, v56, v57
	v_cvt_pk_bf16_f32 v190, v58, v59
	v_cvt_pk_bf16_f32 v191, v60, v61
	v_cvt_pk_bf16_f32 v192, v62, v63
	v_cvt_pk_bf16_f32 v193, v64, v65
	global_store_dwordx4 v222, v[178:181], s[12:13]
	global_store_dwordx4 v222, v[182:185], s[12:13] offset:16
	global_store_dwordx4 v222, v[186:189], s[12:13] offset:64
	global_store_dwordx4 v222, v[190:193], s[12:13] offset:80
	s_waitcnt lgkmcnt(0)
	s_barrier
	s_add_i32 s31, s31, s30
	s_mov_b32 s58, s60
	s_mov_b32 s59, s61
	s_cmpk_lt_i32 s31, 0x400
	s_cbranch_scc1 .Lmrg_task
